# a23 + mla_prep loop condition recomputed before the back edge (the staged write-out uses s_add; keeps the G<256 multi-trip case correct)
# speedup vs baseline: 1.0002x; 1.0002x over previous
.LBB0_535:
	v_ashrrev_i32_e32 v111, 31, v110
	v_lshlrev_b64 v[0:1], 9, v[110:111]
	v_lshl_add_u64 v[0:1], v[106:107], 0, v[0:1]
	global_load_dwordx4 v[24:27], v[0:1], off
	global_load_dwordx4 v[28:31], v[0:1], off offset:16
	global_load_dwordx4 v[36:39], v[0:1], off offset:32
	global_load_dwordx4 v[40:43], v[0:1], off offset:48
	v_ashrrev_i32_e32 v2, 10, v110
	v_and_or_b32 v60, v2, -8, v218
	v_lshlrev_b64 v[2:3], 8, v[110:111]
	v_mad_i64_i32 v[0:1], s[8:9], v110, s18, v[102:103]
	v_lshl_add_u64 v[2:3], v[108:109], 0, v[2:3]
	global_load_dwordx4 v[52:55], v[0:1], off offset:16
	global_load_dwordx4 v[56:59], v[0:1], off
	global_load_dwordx4 v[4:7], v[0:1], off offset:32
	global_load_dwordx4 v[62:65], v[0:1], off offset:48
	global_load_dwordx4 v[8:11], v[0:1], off offset:112
	global_load_dwordx4 v[16:19], v[0:1], off offset:96
	global_load_dwordx4 v[32:35], v[0:1], off offset:80
	global_load_dwordx4 v[48:51], v[0:1], off offset:64
	global_load_dwordx4 v[12:15], v[0:1], off offset:176
	global_load_dwordx4 v[20:23], v[0:1], off offset:160
	global_load_dwordx4 v[66:69], v[2:3], off
	global_load_dwordx4 v[70:73], v[2:3], off offset:16
	global_load_dwordx4 v[44:47], v[0:1], off offset:144
	s_nop 0
	global_load_dwordx4 v[0:3], v[0:1], off offset:128
	v_ashrrev_i32_e32 v61, 31, v60
	v_lshlrev_b64 v[116:117], 13, v[60:61]
	v_and_or_b32 v116, v110, s17, v116
	v_lshlrev_b64 v[80:81], 6, v[110:111]
	v_lshl_add_u64 v[120:121], s[38:39], 0, v[80:81]
	v_lshl_add_u64 v[118:119], s[22:23], 0, v[80:81]
	s_add_i32 s40, s40, s28
	s_cmpk_lt_i32 s40, 0x100
	s_waitcnt vmcnt(17)
	v_and_b32_e32 v61, 0xffff0000, v25
	s_waitcnt vmcnt(16)
	v_lshlrev_b32_e32 v77, 16, v29
	v_lshlrev_b32_e32 v76, 16, v28
	v_and_b32_e32 v29, 0xffff0000, v29
	v_and_b32_e32 v28, 0xffff0000, v28
	s_waitcnt vmcnt(15)
	v_lshlrev_b32_e32 v82, 16, v36
	v_and_b32_e32 v83, 0xffff0000, v36
	v_lshlrev_b32_e32 v36, 16, v37
	v_and_b32_e32 v37, 0xffff0000, v37
	s_waitcnt vmcnt(14)
	v_lshlrev_b32_e32 v90, 16, v41
	v_and_b32_e32 v91, 0xffff0000, v41
	v_lshlrev_b32_e32 v41, 16, v43
	v_lshlrev_b32_e32 v85, 16, v40
	v_and_b32_e32 v87, 0xffff0000, v40
	v_pk_mov_b32 v[88:89], v[38:39], v[42:43] op_sel:[1,0]
	v_pk_mul_f32 v[28:29], v[28:29], v[28:29]
	v_mul_f32_e32 v93, v90, v90
	v_mul_f32_e32 v91, v91, v91
	v_mul_f32_e32 v40, v83, v83
	v_mul_f32_e32 v90, v37, v37
	v_lshlrev_b32_e32 v60, 16, v25
	v_lshlrev_b32_e32 v75, 16, v24
	v_and_b32_e32 v25, 0xffff0000, v24
	v_and_b32_e32 v24, 0xffff0000, v26
	v_and_b32_e32 v92, 0xffff0000, v43
	v_lshlrev_b32_e32 v84, 16, v38
	v_and_b32_e32 v86, 0xffff0000, v38
	v_lshlrev_b32_e32 v43, 16, v42
	v_lshlrev_b32_e32 v42, 16, v39
	v_mul_f32_e32 v38, v61, v61
	v_and_b32_e32 v39, 0xffff0000, v89
	v_pk_fma_f32 v[28:29], v[76:77], v[76:77], v[28:29]
	v_pk_fma_f32 v[76:77], v[82:83], v[82:83], v[40:41] op_sel_hi:[1,1,0]
	v_pk_fma_f32 v[36:37], v[36:37], v[36:37], v[90:91] op_sel_hi:[1,1,0]
	v_lshlrev_b32_e32 v74, 16, v26
	v_pk_mul_f32 v[24:25], v[24:25], v[24:25]
	v_pk_mul_f32 v[86:87], v[86:87], v[86:87]
	v_pk_fma_f32 v[60:61], v[60:61], v[60:61], v[38:39] op_sel_hi:[1,1,0]
	v_mov_b32_e32 v77, v93
	v_mov_b32_e32 v37, v91
	v_and_b32_e32 v38, 0xffff0000, v88
	v_pk_fma_f32 v[24:25], v[74:75], v[74:75], v[24:25]
	v_pk_fma_f32 v[74:75], v[84:85], v[84:85], v[86:87]
	v_pk_add_f32 v[36:37], v[76:77], v[36:37]
	v_pk_mul_f32 v[38:39], v[38:39], v[38:39]
	v_lshlrev_b32_e32 v26, 16, v27
	v_and_b32_e32 v27, 0xffff0000, v27
	v_pk_add_f32 v[36:37], v[74:75], v[36:37]
	v_pk_fma_f32 v[38:39], v[42:43], v[42:43], v[38:39]
	v_lshlrev_b32_e32 v79, 16, v31
	v_lshlrev_b32_e32 v78, 16, v30
	v_and_b32_e32 v31, 0xffff0000, v31
	v_and_b32_e32 v30, 0xffff0000, v30
	v_pk_add_f32 v[60:61], v[24:25], v[60:61] op_sel:[1,0] op_sel_hi:[0,1]
	v_pk_add_f32 v[36:37], v[38:39], v[36:37]
	v_mul_f32_e32 v38, v27, v27
	v_pk_mul_f32 v[30:31], v[30:31], v[30:31]
	v_pk_add_f32 v[24:25], v[24:25], v[60:61]
	v_pk_fma_f32 v[26:27], v[26:27], v[26:27], v[38:39] op_sel_hi:[1,1,0]
	v_pk_fma_f32 v[30:31], v[78:79], v[78:79], v[30:31]
	v_pk_add_f32 v[28:29], v[28:29], v[28:29] op_sel:[0,1] op_sel_hi:[1,0]
	v_mov_b32_e32 v40, v26
	v_mov_b32_e32 v38, v24
	v_mov_b32_e32 v39, v41
	v_pk_add_f32 v[28:29], v[30:31], v[28:29]
	v_pk_add_f32 v[24:25], v[26:27], v[24:25]
	v_pk_mul_f32 v[26:27], v[40:41], v[38:39]
	v_mul_f32_e32 v92, v92, v92
	v_mov_b32_e32 v25, v27
	v_pk_add_f32 v[26:27], v[30:31], v[28:29] op_sel:[1,0] op_sel_hi:[0,1]
	v_mov_b32_e32 v27, v92
	v_pk_add_f32 v[24:25], v[24:25], v[26:27]
	s_waitcnt vmcnt(2)
	v_and_b32_e32 v27, 0xffff0000, v70
	v_pk_add_f32 v[24:25], v[24:25], v[36:37]
	v_and_b32_e32 v26, 0xffff0000, v66
	v_add_f32_e32 v30, v24, v25
	v_lshlrev_b32_e32 v25, 16, v70
	v_lshlrev_b32_e32 v24, 16, v66
	v_pk_mul_f32 v[26:27], v[26:27], v[26:27]
	v_and_b32_e32 v29, 0xffff0000, v71
	v_and_b32_e32 v28, 0xffff0000, v67
	v_pk_fma_f32 v[24:25], v[24:25], v[24:25], v[26:27]
	v_lshlrev_b32_e32 v27, 16, v71
	v_lshlrev_b32_e32 v26, 16, v67
	v_pk_mul_f32 v[28:29], v[28:29], v[28:29]
	v_and_b32_e32 v161, 0xffff0000, v52
	v_pk_fma_f32 v[26:27], v[26:27], v[26:27], v[28:29]
	v_and_b32_e32 v29, 0xffff0000, v72
	v_and_b32_e32 v28, 0xffff0000, v68
	v_pk_add_f32 v[24:25], v[24:25], v[26:27]
	v_lshlrev_b32_e32 v27, 16, v72
	v_lshlrev_b32_e32 v26, 16, v68
	v_pk_mul_f32 v[28:29], v[28:29], v[28:29]
	v_lshlrev_b32_e32 v160, 16, v52
	v_pk_fma_f32 v[26:27], v[26:27], v[26:27], v[28:29]
	v_and_b32_e32 v29, 0xffff0000, v73
	v_and_b32_e32 v28, 0xffff0000, v69
	v_pk_add_f32 v[24:25], v[26:27], v[24:25]
	v_lshlrev_b32_e32 v27, 16, v73
	v_lshlrev_b32_e32 v26, 16, v69
	v_pk_mul_f32 v[28:29], v[28:29], v[28:29]
	v_and_b32_e32 v163, 0xffff0000, v53
	v_pk_fma_f32 v[26:27], v[26:27], v[26:27], v[28:29]
	v_lshlrev_b32_e32 v162, 16, v53
	v_pk_add_f32 v[24:25], v[26:27], v[24:25]
	v_and_b32_e32 v85, 0xffff0000, v63
	v_add_f32_e32 v28, v24, v25
	v_mul_f32_e32 v24, v161, v161
	v_pk_fma_f32 v[60:61], v[160:161], v[160:161], v[24:25] op_sel_hi:[1,1,0]
	v_mul_f32_e32 v24, v163, v163
	v_and_b32_e32 v84, 0xffff0000, v62
	ds_swizzle_b32 v29, v30 offset:swizzle(SWAP,1)
	v_pk_fma_f32 v[52:53], v[162:163], v[162:163], v[24:25] op_sel_hi:[1,1,0]
	v_lshlrev_b32_e32 v123, 16, v63
	v_lshlrev_b32_e32 v122, 16, v62
	v_pk_mul_f32 v[24:25], v[84:85], v[84:85]
	v_and_b32_e32 v87, 0xffff0000, v65
	v_and_b32_e32 v86, 0xffff0000, v64
	v_pk_fma_f32 v[24:25], v[122:123], v[122:123], v[24:25]
	v_lshlrev_b32_e32 v129, 16, v65
	v_lshlrev_b32_e32 v128, 16, v64
	v_pk_mul_f32 v[26:27], v[86:87], v[86:87]
	v_pk_add_f32 v[24:25], v[24:25], v[24:25] op_sel:[0,1] op_sel_hi:[1,0]
	v_pk_fma_f32 v[26:27], v[128:129], v[128:129], v[26:27]
	v_and_b32_e32 v167, 0xffff0000, v48
	v_pk_add_f32 v[24:25], v[26:27], v[24:25]
	v_lshlrev_b32_e32 v166, 16, v48
	v_pk_add_f32 v[184:185], v[26:27], v[24:25] op_sel:[1,0] op_sel_hi:[0,1]
	s_waitcnt lgkmcnt(0)
	v_add_f32_e32 v25, v30, v29
	ds_swizzle_b32 v26, v25 offset:swizzle(SWAP,2)
	v_mul_f32_e32 v24, v167, v167
	v_pk_fma_f32 v[72:73], v[166:167], v[166:167], v[24:25] op_sel_hi:[1,1,0]
	v_and_b32_e32 v191, 0xffff0000, v58
	v_and_b32_e32 v195, 0xffff0000, v56
	s_waitcnt lgkmcnt(0)
	v_add_f32_e32 v25, v25, v26
	ds_swizzle_b32 v26, v25 offset:swizzle(SWAP,4)
	v_lshlrev_b32_e32 v188, 16, v59
	v_and_b32_e32 v189, 0xffff0000, v59
	v_lshlrev_b32_e32 v190, 16, v58
	v_and_b32_e32 v193, 0xffff0000, v57
	v_lshlrev_b32_e32 v194, 16, v56
	v_mov_b32_e32 v58, v191
	v_mov_b32_e32 v59, v195
	v_lshlrev_b32_e32 v192, 16, v57
	v_mul_f32_e32 v48, v193, v193
	v_mov_b32_e32 v56, v190
	v_mov_b32_e32 v57, v194
	v_pk_mul_f32 v[58:59], v[58:59], v[58:59]
	v_lshlrev_b32_e32 v170, 16, v49
	ds_swizzle_b32 v27, v28 offset:swizzle(SWAP,1)
	v_and_b32_e32 v171, 0xffff0000, v49
	v_pk_fma_f32 v[48:49], v[192:193], v[192:193], v[48:49] op_sel_hi:[1,1,0]
	v_pk_fma_f32 v[56:57], v[56:57], v[56:57], v[58:59]
	v_and_b32_e32 v155, 0xffff0000, v4
	v_pk_add_f32 v[48:49], v[56:57], v[48:49] op_sel:[1,0] op_sel_hi:[0,1]
	v_and_b32_e32 v154, 0xffff0000, v54
	v_mul_f32_e32 v24, v171, v171
	v_pk_add_f32 v[56:57], v[56:57], v[48:49]
	v_lshlrev_b32_e32 v159, 16, v4
	v_lshlrev_b32_e32 v158, 16, v54
	v_pk_mul_f32 v[48:49], v[154:155], v[154:155]
	v_pk_fma_f32 v[76:77], v[170:171], v[170:171], v[24:25] op_sel_hi:[1,1,0]
	s_waitcnt lgkmcnt(1)
	v_add_f32_e32 v24, v25, v26
	v_pk_fma_f32 v[58:59], v[158:159], v[158:159], v[48:49]
	v_pk_mov_b32 v[48:49], v[54:55], v[6:7] op_sel:[1,0]
	v_fmamk_f32 v24, v24, 0x3b800000, v100
	v_and_b32_e32 v157, 0xffff0000, v49
	v_and_b32_e32 v156, 0xffff0000, v48
	s_waitcnt lgkmcnt(0)
	v_add_f32_e32 v25, v28, v27
	v_mul_f32_e32 v27, 0x4b800000, v24
	v_cmp_gt_f32_e32 vcc, s19, v24
	v_lshlrev_b32_e32 v173, 16, v6
	v_lshlrev_b32_e32 v172, 16, v55
	v_pk_mul_f32 v[48:49], v[156:157], v[156:157]
	s_waitcnt vmcnt(0)
	v_and_b32_e32 v145, 0xffff0000, v0
	v_and_b32_e32 v144, 0xffff0000, v50
	ds_swizzle_b32 v26, v25 offset:swizzle(SWAP,2)
	v_cndmask_b32_e32 v24, v24, v27, vcc
	v_pk_fma_f32 v[54:55], v[172:173], v[172:173], v[48:49]
	v_lshlrev_b32_e32 v143, 16, v0
	v_lshlrev_b32_e32 v142, 16, v50
	v_pk_mul_f32 v[48:49], v[144:145], v[144:145]
	v_rsq_f32_e32 v24, v24
	v_pk_fma_f32 v[202:203], v[142:143], v[142:143], v[48:49]
	v_pk_mov_b32 v[48:49], v[50:51], v[2:3] op_sel:[1,0]
	v_lshlrev_b32_e32 v139, 16, v2
	v_and_b32_e32 v141, 0xffff0000, v49
	v_and_b32_e32 v140, 0xffff0000, v48
	v_lshlrev_b32_e32 v138, 16, v51
	v_pk_mul_f32 v[48:49], v[140:141], v[140:141]
	v_and_b32_e32 v99, 0xffff0000, v44
	v_and_b32_e32 v98, 0xffff0000, v32
	v_and_b32_e32 v91, 0xffff0000, v45
	v_and_b32_e32 v90, 0xffff0000, v33
	v_pk_fma_f32 v[204:205], v[138:139], v[138:139], v[48:49]
	v_lshlrev_b32_e32 v97, 16, v44
	v_lshlrev_b32_e32 v96, 16, v32
	v_pk_mul_f32 v[48:49], v[98:99], v[98:99]
	v_lshlrev_b32_e32 v89, 16, v45
	v_lshlrev_b32_e32 v88, 16, v33
	v_pk_mul_f32 v[32:33], v[90:91], v[90:91]
	v_and_b32_e32 v127, 0xffff0000, v46
	v_and_b32_e32 v126, 0xffff0000, v34
	s_waitcnt lgkmcnt(0)
	v_add_f32_e32 v75, v25, v26
	v_mul_f32_e32 v25, 0x45800000, v24
	v_pk_fma_f32 v[48:49], v[96:97], v[96:97], v[48:49]
	v_pk_fma_f32 v[32:33], v[88:89], v[88:89], v[32:33]
	v_lshlrev_b32_e32 v125, 16, v46
	v_lshlrev_b32_e32 v124, 16, v34
	v_pk_mul_f32 v[44:45], v[126:127], v[126:127]
	v_and_b32_e32 v95, 0xffff0000, v47
	v_and_b32_e32 v94, 0xffff0000, v35
	v_cndmask_b32_e32 v219, v24, v25, vcc
	global_load_dwordx4 v[24:27], v101, s[44:45] offset:48
	global_load_dwordx4 v[28:31], v101, s[44:45] offset:32
	global_load_dwordx4 v[36:39], v101, s[44:45] offset:16
	global_load_dwordx4 v[40:43], v101, s[44:45]
	v_pk_add_f32 v[32:33], v[48:49], v[32:33]
	v_pk_fma_f32 v[44:45], v[124:125], v[124:125], v[44:45]
	v_lshlrev_b32_e32 v93, 16, v47
	v_lshlrev_b32_e32 v92, 16, v35
	v_pk_mul_f32 v[34:35], v[94:95], v[94:95]
	v_pk_add_f32 v[32:33], v[44:45], v[32:33]
	v_pk_fma_f32 v[34:35], v[92:93], v[92:93], v[34:35]
	v_and_b32_e32 v179, 0xffff0000, v20
	v_and_b32_e32 v178, 0xffff0000, v16
	v_and_b32_e32 v169, 0xffff0000, v21
	v_and_b32_e32 v168, 0xffff0000, v17
	v_pk_add_f32 v[32:33], v[34:35], v[32:33]
	v_lshlrev_b32_e32 v177, 16, v20
	v_lshlrev_b32_e32 v176, 16, v16
	v_pk_mul_f32 v[34:35], v[178:179], v[178:179]
	v_lshlrev_b32_e32 v165, 16, v21
	v_lshlrev_b32_e32 v164, 16, v17
	v_pk_mul_f32 v[16:17], v[168:169], v[168:169]
	v_and_b32_e32 v183, 0xffff0000, v22
	v_and_b32_e32 v182, 0xffff0000, v18
	v_pk_fma_f32 v[34:35], v[176:177], v[176:177], v[34:35]
	v_pk_fma_f32 v[16:17], v[164:165], v[164:165], v[16:17]
	v_lshlrev_b32_e32 v181, 16, v22
	v_lshlrev_b32_e32 v180, 16, v18
	v_pk_mul_f32 v[20:21], v[182:183], v[182:183]
	v_and_b32_e32 v175, 0xffff0000, v23
	v_and_b32_e32 v174, 0xffff0000, v19
	v_pk_add_f32 v[16:17], v[34:35], v[16:17]
	v_pk_fma_f32 v[20:21], v[180:181], v[180:181], v[20:21]
	v_lshlrev_b32_e32 v187, 16, v23
	v_lshlrev_b32_e32 v186, 16, v19
	v_pk_mul_f32 v[18:19], v[174:175], v[174:175]
	v_pk_add_f32 v[16:17], v[20:21], v[16:17]
	v_pk_fma_f32 v[18:19], v[186:187], v[186:187], v[18:19]
	v_and_b32_e32 v149, 0xffff0000, v12
	v_and_b32_e32 v148, 0xffff0000, v8
	v_and_b32_e32 v133, 0xffff0000, v13
	v_and_b32_e32 v132, 0xffff0000, v9
	v_pk_add_f32 v[34:35], v[18:19], v[16:17]
	v_lshlrev_b32_e32 v147, 16, v12
	v_lshlrev_b32_e32 v146, 16, v8
	v_pk_mul_f32 v[16:17], v[148:149], v[148:149]
	v_lshlrev_b32_e32 v131, 16, v13
	v_lshlrev_b32_e32 v130, 16, v9
	v_pk_mul_f32 v[8:9], v[132:133], v[132:133]
	v_pk_fma_f32 v[16:17], v[146:147], v[146:147], v[16:17]
	v_pk_fma_f32 v[8:9], v[130:131], v[130:131], v[8:9]
	v_and_b32_e32 v153, 0xffff0000, v14
	v_pk_add_f32 v[8:9], v[16:17], v[8:9]
	global_load_dwordx4 v[16:19], v101, s[44:45] offset:112
	global_load_dwordx4 v[20:23], v101, s[44:45] offset:96
	global_load_dwordx4 v[44:47], v101, s[44:45] offset:80
	global_load_dwordx4 v[48:51], v101, s[44:45] offset:64
	global_load_dwordx4 v[208:211], v101, s[44:45] offset:176
	global_load_dwordx4 v[212:215], v101, s[44:45] offset:160
	global_load_dwordx4 v[220:223], v101, s[44:45] offset:144
	global_load_dwordx4 v[224:227], v101, s[44:45] offset:128
	v_and_b32_e32 v152, 0xffff0000, v10
	v_lshlrev_b32_e32 v151, 16, v14
	v_lshlrev_b32_e32 v150, 16, v10
	v_pk_mul_f32 v[12:13], v[152:153], v[152:153]
	v_and_b32_e32 v137, 0xffff0000, v15
	v_and_b32_e32 v136, 0xffff0000, v11
	v_mul_f32_e32 v62, v189, v189
	v_pk_fma_f32 v[12:13], v[150:151], v[150:151], v[12:13]
	v_lshlrev_b32_e32 v135, 16, v15
	v_lshlrev_b32_e32 v134, 16, v11
	v_pk_mul_f32 v[10:11], v[136:137], v[136:137]
	v_lshlrev_b32_e32 v196, 16, v7
	v_and_b32_e32 v7, 0xffff0000, v7
	v_lshlrev_b32_e32 v198, 16, v5
	v_and_b32_e32 v199, 0xffff0000, v5
	v_mov_b32_e32 v63, v62
	v_pk_add_f32 v[8:9], v[12:13], v[8:9]
	v_pk_fma_f32 v[10:11], v[134:135], v[134:135], v[10:11]
	v_mov_b32_e32 v197, v7
	v_pk_mul_f32 v[4:5], v[198:199], v[198:199]
	v_pk_add_f32 v[216:217], v[10:11], v[8:9]
	v_and_b32_e32 v6, s0, v6
	v_pk_mov_b32 v[8:9], v[62:63], v[196:197] op_sel:[1,0]
	v_mov_b32_e32 v61, v4
	v_mov_b32_e32 v53, v5
	v_pk_mul_f32 v[6:7], v[6:7], v[6:7]
	v_pk_fma_f32 v[10:11], v[188:189], v[188:189], v[8:9]
	v_pk_mul_f32 v[8:9], v[196:197], v[8:9] op_sel_hi:[0,1]
	v_pk_add_f32 v[4:5], v[60:61], v[52:53]
	v_mov_b32_e32 v11, v9
	v_mov_b32_e32 v57, v7
	v_pk_add_f32 v[4:5], v[58:59], v[4:5]
	v_pk_add_f32 v[6:7], v[10:11], v[56:57]
	v_pk_add_f32 v[4:5], v[54:55], v[4:5]
	v_lshlrev_b32_e32 v200, 16, v3
	v_pk_add_f32 v[4:5], v[6:7], v[4:5]
	v_and_b32_e32 v201, 0xffff0000, v3
	v_pk_add_f32 v[206:207], v[4:5], v[4:5] op_sel:[0,1] op_sel_hi:[1,0]
	v_pk_mul_f32 v[2:3], v[200:201], v[200:201]
	ds_swizzle_b32 v79, v75 offset:swizzle(SWAP,4)
	v_mov_b32_e32 v185, v3
	v_mov_b32_e32 v207, v2
	v_pk_add_f32 v[2:3], v[206:207], v[184:185]
	v_lshlrev_b32_e32 v206, 16, v1
	v_and_b32_e32 v207, 0xffff0000, v1
	v_pk_mul_f32 v[0:1], v[206:207], v[206:207]
	v_mul_f32_e32 v74, v219, v219
	v_mov_b32_e32 v73, v0
	v_mov_b32_e32 v77, v1
	v_pk_add_f32 v[0:1], v[72:73], v[76:77]
	v_mov_b32_e32 v240, v88
	v_pk_add_f32 v[0:1], v[202:203], v[0:1]
	v_mov_b32_e32 v241, v90
	v_pk_add_f32 v[0:1], v[204:205], v[0:1]
	v_mad_u64_u32 v[82:83], s[8:9], v116, s35, v[112:113]
	v_pk_add_f32 v[0:1], v[2:3], v[0:1]
	v_mad_i32_i24 v83, v117, s35, v83
	v_pk_add_f32 v[0:1], v[0:1], v[32:33]
	v_mov_b32_e32 v228, v158
	v_pk_add_f32 v[0:1], v[0:1], v[34:35]
	v_mov_b32_e32 v229, v154
	v_pk_add_f32 v[0:1], v[0:1], v[216:217]
	global_load_dwordx4 v[12:15], v101, s[44:45] offset:240
	global_load_dwordx4 v[56:59], v101, s[44:45] offset:224
	global_load_dwordx4 v[64:67], v101, s[44:45] offset:208
	global_load_dwordx4 v[68:71], v101, s[44:45] offset:192
	global_load_dwordx4 v[4:7], v101, s[44:45] offset:304
	global_load_dwordx4 v[8:11], v101, s[44:45] offset:288
	global_load_dwordx4 v[60:63], v101, s[44:45] offset:256
	global_load_dwordx4 v[52:55], v101, s[44:45] offset:272
	v_pk_mul_f32 v[0:1], v[0:1], v[74:75] op_sel_hi:[1,0]
	v_mov_b32_e32 v230, v172
	v_mov_b32_e32 v74, v0
	v_mov_b32_e32 v78, v1
	s_waitcnt lgkmcnt(0)
	v_pk_add_f32 v[0:1], v[74:75], v[78:79]
	v_mov_b32_e32 v231, v156
	v_pk_fma_f32 v[184:185], v[0:1], s[14:15], v[100:101] op_sel_hi:[1,1,0]
	v_mov_b32_e32 v232, v142
	v_mul_f32_e32 v0, 0x4b800000, v184
	v_cmp_gt_f32_e32 vcc, s19, v184
	v_mov_b32_e32 v233, v144
	v_mov_b32_e32 v234, v138
	v_cndmask_b32_e32 v0, v184, v0, vcc
	v_rsq_f32_e32 v88, v0
	global_load_dwordx4 v[0:3], v101, s[44:45] offset:368
	global_load_dwordx4 v[32:35], v101, s[44:45] offset:352
	global_load_dwordx4 v[76:79], v101, s[44:45] offset:320
	global_load_dwordx4 v[72:75], v101, s[44:45] offset:336
	v_mov_b32_e32 v235, v140
	v_mov_b32_e32 v236, v96
	v_mul_f32_e32 v90, 0x45800000, v88
	v_cndmask_b32_e32 v88, v88, v90, vcc
	v_mul_f32_e32 v88, 0x3e16c740, v88
	v_mul_f32_e32 v88, v219, v88
	s_waitcnt vmcnt(21)
	v_pk_mul_f32 v[36:37], v[36:37], v[88:89] op_sel_hi:[1,0]
	s_waitcnt vmcnt(20)
	v_pk_mul_f32 v[40:41], v[40:41], v[88:89] op_sel_hi:[1,0]
	v_pk_mul_f32 v[190:191], v[36:37], v[190:191]
	v_pk_mul_f32 v[36:37], v[42:43], v[88:89] op_sel_hi:[1,0]
	v_pk_mul_f32 v[40:41], v[40:41], v[194:195]
	v_pk_mul_f32 v[42:43], v[36:37], v[192:193]
	v_pk_mul_f32 v[36:37], v[38:39], v[88:89] op_sel_hi:[1,0]
	v_cvt_pk_bf16_f32 v38, v190, v191
	v_pk_mul_f32 v[188:189], v[36:37], v[188:189]
	v_cvt_pk_bf16_f32 v36, v40, v41
	v_cvt_pk_bf16_f32 v37, v42, v43
	v_cvt_pk_bf16_f32 v39, v188, v189
	v_pk_mul_f32 v[24:25], v[24:25], v[88:89] op_sel_hi:[1,0]
	s_mul_i32 s57, s33, 0xc0
	v_mbcnt_lo_u32_b32 v244, -1, 0
	v_mbcnt_hi_u32_b32 v244, -1, v244
	v_mul_u32_u24_e32 v244, 0xc0, v244
	v_add_u32_e32 v244, s57, v244
	ds_write_b128 v244, v[36:39]
	v_pk_mul_f32 v[28:29], v[28:29], v[88:89] op_sel_hi:[1,0]
	v_mov_b32_e32 v237, v98
	v_pk_mul_f32 v[36:37], v[24:25], v[228:229]
	v_pk_mul_f32 v[24:25], v[30:31], v[88:89] op_sel_hi:[1,0]
	v_pk_mul_f32 v[28:29], v[28:29], v[160:161]
	v_pk_mul_f32 v[30:31], v[24:25], v[162:163]
	v_pk_mul_f32 v[24:25], v[26:27], v[88:89] op_sel_hi:[1,0]
	v_cvt_pk_bf16_f32 v26, v36, v37
	v_pk_mul_f32 v[38:39], v[24:25], v[230:231]
	v_cvt_pk_bf16_f32 v24, v28, v29
	v_cvt_pk_bf16_f32 v25, v30, v31
	v_cvt_pk_bf16_f32 v27, v38, v39
	ds_write_b128 v244, v[24:27] offset:16
	s_waitcnt vmcnt(12)
	v_pk_mul_f32 v[28:29], v[226:227], v[88:89] op_sel_hi:[1,0]
	v_pk_mul_f32 v[30:31], v[222:223], v[88:89] op_sel_hi:[1,0]
	v_pk_mul_f32 v[24:25], v[224:225], v[88:89] op_sel_hi:[1,0]
	v_pk_mul_f32 v[26:27], v[220:221], v[88:89] op_sel_hi:[1,0]
	v_pk_mul_f32 v[24:25], v[24:25], v[166:167]
	v_pk_mul_f32 v[26:27], v[26:27], v[232:233]
	v_pk_mul_f32 v[28:29], v[28:29], v[170:171]
	v_pk_mul_f32 v[30:31], v[30:31], v[234:235]
	v_cvt_pk_bf16_f32 v24, v24, v25
	v_cvt_pk_bf16_f32 v25, v28, v29
	v_cvt_pk_bf16_f32 v26, v26, v27
	v_cvt_pk_bf16_f32 v27, v30, v31
	v_mov_b32_e32 v238, v124
	v_mov_b32_e32 v239, v126
	v_mov_b32_e32 v242, v92
	v_mov_b32_e32 v243, v94
	ds_write_b128 v244, v[24:27] offset:64
	v_pk_mul_f32 v[28:29], v[88:89], v[214:215] op_sel_hi:[0,1]
	v_pk_mul_f32 v[30:31], v[88:89], v[210:211] op_sel_hi:[0,1]
	v_pk_mul_f32 v[24:25], v[88:89], v[212:213] op_sel_hi:[0,1]
	v_pk_mul_f32 v[26:27], v[88:89], v[208:209] op_sel_hi:[0,1]
	v_pk_mul_f32 v[24:25], v[24:25], v[236:237]
	v_pk_mul_f32 v[26:27], v[26:27], v[238:239]
	v_pk_mul_f32 v[28:29], v[28:29], v[240:241]
	v_pk_mul_f32 v[30:31], v[30:31], v[242:243]
	v_cvt_pk_bf16_f32 v24, v24, v25
	v_cvt_pk_bf16_f32 v25, v28, v29
	v_cvt_pk_bf16_f32 v26, v26, v27
	v_cvt_pk_bf16_f32 v27, v30, v31
	global_load_dwordx4 v[28:31], v[120:121], off
	global_load_dwordx4 v[36:39], v[118:119], off
	v_mov_b32_e32 v156, v173
	ds_write_b128 v244, v[24:27] offset:80
	global_load_dwordx4 v[24:27], v[118:119], off offset:16
	s_nop 0
	global_load_dwordx4 v[40:43], v[120:121], off offset:16
	v_mov_b32_e32 v154, v159
	v_pk_mul_f32 v[48:49], v[48:49], v[88:89] op_sel_hi:[1,0]
	v_pk_mul_f32 v[44:45], v[44:45], v[88:89] op_sel_hi:[1,0]
	v_pk_mul_f32 v[48:49], v[48:49], v[154:155]
	v_pk_mul_f32 v[154:155], v[44:45], v[156:157]
	v_pk_mul_f32 v[44:45], v[50:51], v[88:89] op_sel_hi:[1,0]
	v_mov_b32_e32 v160, v128
	v_pk_mul_f32 v[50:51], v[44:45], v[198:199]
	v_pk_mul_f32 v[44:45], v[46:47], v[88:89] op_sel_hi:[1,0]
	v_mov_b32_e32 v161, v86
	v_pk_mul_f32 v[156:157], v[44:45], v[196:197]
	v_cvt_pk_bf16_f32 v44, v48, v49
	v_cvt_pk_bf16_f32 v45, v50, v51
	v_cvt_pk_bf16_f32 v46, v154, v155
	v_cvt_pk_bf16_f32 v47, v156, v157
	v_pk_mul_f32 v[16:17], v[16:17], v[88:89] op_sel_hi:[1,0]
	v_mov_b32_e32 v159, v84
	v_mov_b32_e32 v84, v123
	ds_write_b128 v244, v[44:47] offset:32
	v_mov_b32_e32 v158, v122
	v_mov_b32_e32 v86, v129
	v_pk_mul_f32 v[44:45], v[16:17], v[160:161]
	v_pk_mul_f32 v[16:17], v[22:23], v[88:89] op_sel_hi:[1,0]
	v_pk_mul_f32 v[20:21], v[20:21], v[88:89] op_sel_hi:[1,0]
	v_pk_mul_f32 v[22:23], v[16:17], v[84:85]
	v_pk_mul_f32 v[16:17], v[18:19], v[88:89] op_sel_hi:[1,0]
	v_pk_mul_f32 v[20:21], v[20:21], v[158:159]
	v_pk_mul_f32 v[46:47], v[16:17], v[86:87]
	v_cvt_pk_bf16_f32 v16, v20, v21
	v_cvt_pk_bf16_f32 v17, v22, v23
	v_cvt_pk_bf16_f32 v18, v44, v45
	v_cvt_pk_bf16_f32 v19, v46, v47
	v_mov_b32_e32 v122, v176
	v_mov_b32_e32 v123, v178
	v_mov_b32_e32 v128, v180
	v_mov_b32_e32 v129, v182
	v_mov_b32_e32 v162, v164
	v_mov_b32_e32 v163, v168
	v_mov_b32_e32 v166, v186
	v_mov_b32_e32 v167, v174
	ds_write_b128 v244, v[16:19] offset:48
	s_waitcnt vmcnt(12)
	v_pk_mul_f32 v[20:21], v[88:89], v[70:71] op_sel_hi:[0,1]
	v_pk_mul_f32 v[22:23], v[88:89], v[66:67] op_sel_hi:[0,1]
	v_pk_mul_f32 v[16:17], v[88:89], v[68:69] op_sel_hi:[0,1]
	v_pk_mul_f32 v[18:19], v[88:89], v[64:65] op_sel_hi:[0,1]
	v_pk_mul_f32 v[16:17], v[16:17], v[122:123]
	v_pk_mul_f32 v[18:19], v[18:19], v[128:129]
	v_pk_mul_f32 v[20:21], v[20:21], v[162:163]
	v_pk_mul_f32 v[22:23], v[22:23], v[166:167]
	v_cvt_pk_bf16_f32 v16, v16, v17
	v_cvt_pk_bf16_f32 v17, v20, v21
	v_cvt_pk_bf16_f32 v18, v18, v19
	v_cvt_pk_bf16_f32 v19, v22, v23
	v_mov_b32_e32 v182, v181
	v_mov_b32_e32 v170, v146
	v_mov_b32_e32 v171, v148
	ds_write_b128 v244, v[16:19] offset:96
	v_mov_b32_e32 v144, v143
	v_mov_b32_e32 v140, v139
	v_pk_mul_f32 v[16:17], v[88:89], v[56:57] op_sel_hi:[0,1]
	v_pk_mul_f32 v[18:19], v[88:89], v[182:183] op_sel_hi:[0,1]
	v_mov_b32_e32 v172, v150
	v_mov_b32_e32 v173, v152
	v_mov_b32_e32 v174, v187
	v_pk_mul_f32 v[44:45], v[16:17], v[170:171]
	v_pk_mul_f32 v[12:13], v[88:89], v[12:13] op_sel_hi:[0,1]
	v_pk_mul_f32 v[16:17], v[88:89], v[144:145] op_sel_hi:[0,1]
	v_mov_b32_e32 v178, v177
	s_waitcnt vmcnt(4)
	v_pk_mul_f32 v[56:57], v[18:19], v[72:73]
	v_pk_mul_f32 v[18:19], v[88:89], v[140:141] op_sel_hi:[0,1]
	v_pk_mul_f32 v[20:21], v[88:89], v[206:207] op_sel_hi:[0,1]
	v_mov_b32_e32 v168, v165
	v_pk_mul_f32 v[22:23], v[88:89], v[200:201] op_sel_hi:[0,1]
	v_pk_mul_f32 v[46:47], v[12:13], v[172:173]
	v_pk_mul_f32 v[12:13], v[88:89], v[58:59] op_sel_hi:[0,1]
	v_pk_mul_f32 v[48:49], v[16:17], v[60:61]
	v_pk_mul_f32 v[16:17], v[88:89], v[178:179] op_sel_hi:[0,1]
	v_pk_mul_f32 v[52:53], v[18:19], v[52:53]
	v_pk_mul_f32 v[58:59], v[20:21], v[62:63]
	v_pk_mul_f32 v[20:21], v[88:89], v[168:169] op_sel_hi:[0,1]
	v_pk_mul_f32 v[54:55], v[22:23], v[54:55]
	v_pk_mul_f32 v[22:23], v[88:89], v[174:175] op_sel_hi:[0,1]
	v_pk_mul_f32 v[50:51], v[16:17], v[76:77]
	s_waitcnt vmcnt(3)
	v_pk_mul_f32 v[16:17], v[48:49], v[28:29]
	s_waitcnt vmcnt(0)
	v_pk_mul_f32 v[18:19], v[52:53], v[40:41]
	v_pk_mul_f32 v[60:61], v[20:21], v[78:79]
	v_pk_mul_f32 v[20:21], v[58:59], v[30:31]
	v_pk_mul_f32 v[62:63], v[22:23], v[74:75]
	v_pk_mul_f32 v[22:23], v[54:55], v[42:43]
	v_pk_fma_f32 v[16:17], v[50:51], v[36:37], v[16:17]
	v_pk_fma_f32 v[18:19], v[56:57], v[24:25], v[18:19]
	v_pk_fma_f32 v[20:21], v[60:61], v[38:39], v[20:21]
	v_pk_fma_f32 v[22:23], v[62:63], v[26:27], v[22:23]
	v_mov_b32_e32 v188, v130
	v_mov_b32_e32 v189, v132
	v_cvt_pk_bf16_f32 v16, v16, v17
	v_cvt_pk_bf16_f32 v17, v20, v21
	v_cvt_pk_bf16_f32 v18, v18, v19
	v_cvt_pk_bf16_f32 v19, v22, v23
	v_mov_b32_e32 v190, v134
	v_mov_b32_e32 v191, v136
	ds_write_b128 v244, v[16:19] offset:160
	v_pk_mul_f32 v[64:65], v[12:13], v[188:189]
	v_pk_mul_f32 v[12:13], v[88:89], v[14:15] op_sel_hi:[0,1]
	global_load_dwordx4 v[16:19], v[120:121], off offset:32
	global_load_dwordx4 v[20:23], v[118:119], off offset:32
	v_pk_mul_f32 v[66:67], v[12:13], v[190:191]
	v_cvt_pk_bf16_f32 v12, v44, v45
	v_cvt_pk_bf16_f32 v13, v64, v65
	v_cvt_pk_bf16_f32 v14, v46, v47
	v_cvt_pk_bf16_f32 v15, v66, v67
	ds_write_b128 v244, v[12:15] offset:112
	global_load_dwordx4 v[12:15], v[120:121], off offset:48
	s_nop 0
	global_load_dwordx4 v[44:47], v[118:119], off offset:48
	v_pk_mul_f32 v[28:29], v[50:51], v[28:29]
	v_mov_b32_e32 v98, v97
	v_pk_fma_f32 v[28:29], v[48:49], v[36:37], v[28:29] neg_lo:[0,0,1] neg_hi:[0,0,1]
	v_pk_mul_f32 v[36:37], v[56:57], v[40:41]
	v_mov_b32_e32 v148, v147
	v_pk_fma_f32 v[36:37], v[52:53], v[24:25], v[36:37] neg_lo:[0,0,1] neg_hi:[0,0,1]
	v_pk_mul_f32 v[24:25], v[60:61], v[30:31]
	v_mov_b32_e32 v152, v151
	v_pk_fma_f32 v[30:31], v[58:59], v[38:39], v[24:25] neg_lo:[0,0,1] neg_hi:[0,0,1]
	v_pk_mul_f32 v[24:25], v[62:63], v[42:43]
	v_mov_b32_e32 v126, v125
	v_pk_fma_f32 v[38:39], v[54:55], v[26:27], v[24:25] neg_lo:[0,0,1] neg_hi:[0,0,1]
	v_cvt_pk_bf16_f32 v24, v28, v29
	v_cvt_pk_bf16_f32 v25, v30, v31
	v_cvt_pk_bf16_f32 v26, v36, v37
	v_cvt_pk_bf16_f32 v27, v38, v39
	ds_write_b128 v244, v[24:27] offset:128
	v_mov_b32_e32 v90, v89
	v_mov_b32_e32 v132, v131
	v_pk_mul_f32 v[24:25], v[88:89], v[98:99] op_sel_hi:[0,1]
	v_pk_mul_f32 v[8:9], v[24:25], v[8:9]
	v_pk_mul_f32 v[24:25], v[88:89], v[148:149] op_sel_hi:[0,1]
	v_pk_mul_f32 v[24:25], v[24:25], v[32:33]
	v_mov_b32_e32 v94, v93
	v_mov_b32_e32 v136, v135
	v_lshlrev_b64 v[64:65], 11, v[110:111]
	v_lshl_add_u64 v[64:65], v[104:105], 0, v[64:65]
	v_cmp_gt_f32_e32 vcc, s19, v185
	v_lshl_add_u64 v[40:41], s[20:21], 0, v[80:81]
	v_mad_u64_u32 v[124:125], s[8:9], v116, s35, v[114:115]
	v_mad_i32_i24 v125, v117, s35, v125
	v_add_u32_e32 v110, s16, v110
	s_waitcnt vmcnt(3)
	v_pk_mul_f32 v[26:27], v[8:9], v[16:17]
	v_pk_mul_f32 v[16:17], v[24:25], v[16:17]
	s_waitcnt vmcnt(2)
	v_pk_fma_f32 v[26:27], v[24:25], v[20:21], v[26:27]
	v_pk_fma_f32 v[8:9], v[8:9], v[20:21], v[16:17] neg_lo:[0,0,1] neg_hi:[0,0,1]
	v_pk_mul_f32 v[16:17], v[88:89], v[152:153] op_sel_hi:[0,1]
	v_pk_mul_f32 v[0:1], v[16:17], v[0:1]
	v_pk_mul_f32 v[16:17], v[88:89], v[126:127] op_sel_hi:[0,1]
	v_pk_mul_f32 v[4:5], v[16:17], v[4:5]
	s_waitcnt vmcnt(1)
	v_pk_mul_f32 v[16:17], v[0:1], v[12:13]
	s_waitcnt vmcnt(0)
	v_pk_fma_f32 v[16:17], v[4:5], v[44:45], v[16:17] neg_lo:[0,0,1] neg_hi:[0,0,1]
	v_pk_mul_f32 v[4:5], v[4:5], v[12:13]
	s_nop 0
	v_pk_fma_f32 v[4:5], v[0:1], v[44:45], v[4:5]
	v_pk_mul_f32 v[0:1], v[88:89], v[90:91] op_sel_hi:[0,1]
	v_pk_mul_f32 v[0:1], v[0:1], v[10:11]
	v_pk_mul_f32 v[10:11], v[88:89], v[132:133] op_sel_hi:[0,1]
	v_pk_mul_f32 v[10:11], v[10:11], v[34:35]
	v_pk_mul_f32 v[12:13], v[0:1], v[18:19]
	s_nop 0
	v_pk_fma_f32 v[12:13], v[10:11], v[22:23], v[12:13]
	v_pk_mul_f32 v[10:11], v[10:11], v[18:19]
	s_nop 0
	v_pk_fma_f32 v[10:11], v[0:1], v[22:23], v[10:11] neg_lo:[0,0,1] neg_hi:[0,0,1]
	v_pk_mul_f32 v[0:1], v[88:89], v[94:95] op_sel_hi:[0,1]
	v_pk_mul_f32 v[0:1], v[0:1], v[6:7]
	v_pk_mul_f32 v[6:7], v[88:89], v[136:137] op_sel_hi:[0,1]
	v_pk_mul_f32 v[2:3], v[6:7], v[2:3]
	v_pk_mul_f32 v[6:7], v[0:1], v[14:15]
	s_nop 0
	v_pk_fma_f32 v[6:7], v[2:3], v[46:47], v[6:7]
	v_pk_mul_f32 v[2:3], v[2:3], v[14:15]
	s_nop 0
	v_pk_fma_f32 v[14:15], v[0:1], v[46:47], v[2:3] neg_lo:[0,0,1] neg_hi:[0,0,1]
	v_cvt_pk_bf16_f32 v0, v8, v9
	v_cvt_pk_bf16_f32 v1, v10, v11
	v_cvt_pk_bf16_f32 v2, v16, v17
	v_cvt_pk_bf16_f32 v3, v14, v15
	ds_write_b128 v244, v[0:3] offset:144
	s_nop 1
	v_cvt_pk_bf16_f32 v0, v26, v27
	v_cvt_pk_bf16_f32 v1, v12, v13
	v_cvt_pk_bf16_f32 v2, v4, v5
	v_cvt_pk_bf16_f32 v3, v6, v7
	ds_write_b128 v244, v[0:3] offset:176
	v_readfirstlane_b32 s58, v82
	v_readfirstlane_b32 s59, v83
	v_mbcnt_lo_u32_b32 v0, -1, 0
	v_mbcnt_hi_u32_b32 v0, -1, v0
	v_mov_b32_e32 v1, v0
	v_mul_u32_u24_e32 v2, 0xaaab, v1
	v_lshrrev_b32_e32 v2, 22, v2
	v_mul_u32_u24_e32 v3, 0x60, v2
	v_sub_u32_e32 v3, v1, v3
	v_mul_u32_u24_e32 v4, 0x1556, v3
	v_lshrrev_b32_e32 v4, 16, v4
	v_mul_u32_u24_e32 v5, 12, v4
	v_sub_u32_e32 v5, v3, v5
	v_lshl_add_u32 v6, v4, 3, v2
	v_mul_u32_u24_e32 v6, 0xc0, v6
	v_lshl_add_u32 v6, v5, 4, v6
	v_add_u32_e32 v6, s57, v6
	ds_read_b128 v[16:19], v6
	v_mul_u32_u24_e32 v10, 0x180000, v2
	v_lshl_add_u32 v10, v3, 4, v10
	v_add_u32_e32 v1, 0x40, v0
	v_mul_u32_u24_e32 v2, 0xaaab, v1
	v_lshrrev_b32_e32 v2, 22, v2
	v_mul_u32_u24_e32 v3, 0x60, v2
	v_sub_u32_e32 v3, v1, v3
	v_mul_u32_u24_e32 v4, 0x1556, v3
	v_lshrrev_b32_e32 v4, 16, v4
	v_mul_u32_u24_e32 v5, 12, v4
	v_sub_u32_e32 v5, v3, v5
	v_lshl_add_u32 v7, v4, 3, v2
	v_mul_u32_u24_e32 v7, 0xc0, v7
	v_lshl_add_u32 v7, v5, 4, v7
	v_add_u32_e32 v7, s57, v7
	ds_read_b128 v[20:23], v7
	v_mul_u32_u24_e32 v11, 0x180000, v2
	v_lshl_add_u32 v11, v3, 4, v11
	v_add_u32_e32 v1, 0x80, v0
	v_mul_u32_u24_e32 v2, 0xaaab, v1
	v_lshrrev_b32_e32 v2, 22, v2
	v_mul_u32_u24_e32 v3, 0x60, v2
	v_sub_u32_e32 v3, v1, v3
	v_mul_u32_u24_e32 v4, 0x1556, v3
	v_lshrrev_b32_e32 v4, 16, v4
	v_mul_u32_u24_e32 v5, 12, v4
	v_sub_u32_e32 v5, v3, v5
	v_lshl_add_u32 v8, v4, 3, v2
	v_mul_u32_u24_e32 v8, 0xc0, v8
	v_lshl_add_u32 v8, v5, 4, v8
	v_add_u32_e32 v8, s57, v8
	ds_read_b128 v[24:27], v8
	v_mul_u32_u24_e32 v12, 0x180000, v2
	v_lshl_add_u32 v12, v3, 4, v12
	v_add_u32_e32 v1, 0xc0, v0
	v_mul_u32_u24_e32 v2, 0xaaab, v1
	v_lshrrev_b32_e32 v2, 22, v2
	v_mul_u32_u24_e32 v3, 0x60, v2
	v_sub_u32_e32 v3, v1, v3
	v_mul_u32_u24_e32 v4, 0x1556, v3
	v_lshrrev_b32_e32 v4, 16, v4
	v_mul_u32_u24_e32 v5, 12, v4
	v_sub_u32_e32 v5, v3, v5
	v_lshl_add_u32 v9, v4, 3, v2
	v_mul_u32_u24_e32 v9, 0xc0, v9
	v_lshl_add_u32 v9, v5, 4, v9
	v_add_u32_e32 v9, s57, v9
	ds_read_b128 v[28:31], v9
	v_mul_u32_u24_e32 v13, 0x180000, v2
	v_lshl_add_u32 v13, v3, 4, v13
	s_waitcnt lgkmcnt(0)
	global_store_dwordx4 v10, v[16:19], s[58:59]
	global_store_dwordx4 v11, v[20:23], s[58:59]
	global_store_dwordx4 v12, v[24:27], s[58:59]
	global_store_dwordx4 v13, v[28:31], s[58:59]
	v_add_u32_e32 v1, 0x100, v0
	v_mul_u32_u24_e32 v2, 0xaaab, v1
	v_lshrrev_b32_e32 v2, 22, v2
	v_mul_u32_u24_e32 v3, 0x60, v2
	v_sub_u32_e32 v3, v1, v3
	v_mul_u32_u24_e32 v4, 0x1556, v3
	v_lshrrev_b32_e32 v4, 16, v4
	v_mul_u32_u24_e32 v5, 12, v4
	v_sub_u32_e32 v5, v3, v5
	v_lshl_add_u32 v6, v4, 3, v2
	v_mul_u32_u24_e32 v6, 0xc0, v6
	v_lshl_add_u32 v6, v5, 4, v6
	v_add_u32_e32 v6, s57, v6
	ds_read_b128 v[16:19], v6
	v_mul_u32_u24_e32 v10, 0x180000, v2
	v_lshl_add_u32 v10, v3, 4, v10
	v_add_u32_e32 v1, 0x140, v0
	v_mul_u32_u24_e32 v2, 0xaaab, v1
	v_lshrrev_b32_e32 v2, 22, v2
	v_mul_u32_u24_e32 v3, 0x60, v2
	v_sub_u32_e32 v3, v1, v3
	v_mul_u32_u24_e32 v4, 0x1556, v3
	v_lshrrev_b32_e32 v4, 16, v4
	v_mul_u32_u24_e32 v5, 12, v4
	v_sub_u32_e32 v5, v3, v5
	v_lshl_add_u32 v7, v4, 3, v2
	v_mul_u32_u24_e32 v7, 0xc0, v7
	v_lshl_add_u32 v7, v5, 4, v7
	v_add_u32_e32 v7, s57, v7
	ds_read_b128 v[20:23], v7
	v_mul_u32_u24_e32 v11, 0x180000, v2
	v_lshl_add_u32 v11, v3, 4, v11
	v_add_u32_e32 v1, 0x180, v0
	v_mul_u32_u24_e32 v2, 0xaaab, v1
	v_lshrrev_b32_e32 v2, 22, v2
	v_mul_u32_u24_e32 v3, 0x60, v2
	v_sub_u32_e32 v3, v1, v3
	v_mul_u32_u24_e32 v4, 0x1556, v3
	v_lshrrev_b32_e32 v4, 16, v4
	v_mul_u32_u24_e32 v5, 12, v4
	v_sub_u32_e32 v5, v3, v5
	v_lshl_add_u32 v8, v4, 3, v2
	v_mul_u32_u24_e32 v8, 0xc0, v8
	v_lshl_add_u32 v8, v5, 4, v8
	v_add_u32_e32 v8, s57, v8
	ds_read_b128 v[24:27], v8
	v_mul_u32_u24_e32 v12, 0x180000, v2
	v_lshl_add_u32 v12, v3, 4, v12
	v_add_u32_e32 v1, 0x1c0, v0
	v_mul_u32_u24_e32 v2, 0xaaab, v1
	v_lshrrev_b32_e32 v2, 22, v2
	v_mul_u32_u24_e32 v3, 0x60, v2
	v_sub_u32_e32 v3, v1, v3
	v_mul_u32_u24_e32 v4, 0x1556, v3
	v_lshrrev_b32_e32 v4, 16, v4
	v_mul_u32_u24_e32 v5, 12, v4
	v_sub_u32_e32 v5, v3, v5
	v_lshl_add_u32 v9, v4, 3, v2
	v_mul_u32_u24_e32 v9, 0xc0, v9
	v_lshl_add_u32 v9, v5, 4, v9
	v_add_u32_e32 v9, s57, v9
	ds_read_b128 v[28:31], v9
	v_mul_u32_u24_e32 v13, 0x180000, v2
	v_lshl_add_u32 v13, v3, 4, v13
	s_waitcnt lgkmcnt(0)
	global_store_dwordx4 v10, v[16:19], s[58:59]
	global_store_dwordx4 v11, v[20:23], s[58:59]
	global_store_dwordx4 v12, v[24:27], s[58:59]
	global_store_dwordx4 v13, v[28:31], s[58:59]
	v_add_u32_e32 v1, 0x200, v0
	v_mul_u32_u24_e32 v2, 0xaaab, v1
	v_lshrrev_b32_e32 v2, 22, v2
	v_mul_u32_u24_e32 v3, 0x60, v2
	v_sub_u32_e32 v3, v1, v3
	v_mul_u32_u24_e32 v4, 0x1556, v3
	v_lshrrev_b32_e32 v4, 16, v4
	v_mul_u32_u24_e32 v5, 12, v4
	v_sub_u32_e32 v5, v3, v5
	v_lshl_add_u32 v6, v4, 3, v2
	v_mul_u32_u24_e32 v6, 0xc0, v6
	v_lshl_add_u32 v6, v5, 4, v6
	v_add_u32_e32 v6, s57, v6
	ds_read_b128 v[16:19], v6
	v_mul_u32_u24_e32 v10, 0x180000, v2
	v_lshl_add_u32 v10, v3, 4, v10
	v_add_u32_e32 v1, 0x240, v0
	v_mul_u32_u24_e32 v2, 0xaaab, v1
	v_lshrrev_b32_e32 v2, 22, v2
	v_mul_u32_u24_e32 v3, 0x60, v2
	v_sub_u32_e32 v3, v1, v3
	v_mul_u32_u24_e32 v4, 0x1556, v3
	v_lshrrev_b32_e32 v4, 16, v4
	v_mul_u32_u24_e32 v5, 12, v4
	v_sub_u32_e32 v5, v3, v5
	v_lshl_add_u32 v7, v4, 3, v2
	v_mul_u32_u24_e32 v7, 0xc0, v7
	v_lshl_add_u32 v7, v5, 4, v7
	v_add_u32_e32 v7, s57, v7
	ds_read_b128 v[20:23], v7
	v_mul_u32_u24_e32 v11, 0x180000, v2
	v_lshl_add_u32 v11, v3, 4, v11
	v_add_u32_e32 v1, 0x280, v0
	v_mul_u32_u24_e32 v2, 0xaaab, v1
	v_lshrrev_b32_e32 v2, 22, v2
	v_mul_u32_u24_e32 v3, 0x60, v2
	v_sub_u32_e32 v3, v1, v3
	v_mul_u32_u24_e32 v4, 0x1556, v3
	v_lshrrev_b32_e32 v4, 16, v4
	v_mul_u32_u24_e32 v5, 12, v4
	v_sub_u32_e32 v5, v3, v5
	v_lshl_add_u32 v8, v4, 3, v2
	v_mul_u32_u24_e32 v8, 0xc0, v8
	v_lshl_add_u32 v8, v5, 4, v8
	v_add_u32_e32 v8, s57, v8
	ds_read_b128 v[24:27], v8
	v_mul_u32_u24_e32 v12, 0x180000, v2
	v_lshl_add_u32 v12, v3, 4, v12
	v_add_u32_e32 v1, 0x2c0, v0
	v_mul_u32_u24_e32 v2, 0xaaab, v1
	v_lshrrev_b32_e32 v2, 22, v2
	v_mul_u32_u24_e32 v3, 0x60, v2
	v_sub_u32_e32 v3, v1, v3
	v_mul_u32_u24_e32 v4, 0x1556, v3
	v_lshrrev_b32_e32 v4, 16, v4
	v_mul_u32_u24_e32 v5, 12, v4
	v_sub_u32_e32 v5, v3, v5
	v_lshl_add_u32 v9, v4, 3, v2
	v_mul_u32_u24_e32 v9, 0xc0, v9
	v_lshl_add_u32 v9, v5, 4, v9
	v_add_u32_e32 v9, s57, v9
	ds_read_b128 v[28:31], v9
	v_mul_u32_u24_e32 v13, 0x180000, v2
	v_lshl_add_u32 v13, v3, 4, v13
	s_waitcnt lgkmcnt(0)
	global_store_dwordx4 v10, v[16:19], s[58:59]
	global_store_dwordx4 v11, v[20:23], s[58:59]
	global_store_dwordx4 v12, v[24:27], s[58:59]
	global_store_dwordx4 v13, v[28:31], s[58:59]
	global_load_dwordx4 v[70:73], v[64:65], off offset:16
	global_load_dwordx4 v[32:35], v[64:65], off offset:48
	global_load_dwordx4 v[74:77], v[64:65], off offset:64
	global_load_dwordx4 v[84:87], v[64:65], off
	global_load_dwordx4 v[52:55], v[64:65], off offset:32
	v_mul_f32_e32 v0, 0x4b800000, v185
	global_load_dwordx4 v[88:91], v[64:65], off offset:80
	v_cndmask_b32_e32 v0, v185, v0, vcc
	v_rsq_f32_e32 v42, v0
	global_load_dwordx4 v[16:19], v[64:65], off offset:176
	global_load_dwordx4 v[20:23], v[64:65], off offset:160
	global_load_dwordx4 v[24:27], v[64:65], off offset:144
	global_load_dwordx4 v[28:31], v[64:65], off offset:128
	global_load_dwordx4 v[56:59], v[64:65], off offset:112
	global_load_dwordx4 v[150:153], v[64:65], off offset:96
	global_load_dwordx4 v[130:133], v[40:41], off offset:16
	global_load_dwordx4 v[36:39], v[40:41], off
	global_load_dwordx4 v[0:3], v[64:65], off offset:240
	global_load_dwordx4 v[4:7], v[64:65], off offset:224
	global_load_dwordx4 v[8:11], v[64:65], off offset:208
	global_load_dwordx4 v[12:15], v[64:65], off offset:192
	global_load_dwordx4 v[60:63], v[40:41], off offset:48
	global_load_dwordx4 v[154:157], v[40:41], off offset:32
	v_mul_f32_e32 v43, 0x45800000, v42
	v_cndmask_b32_e32 v122, v42, v43, vcc
	v_mul_f32_e32 v111, v122, v122
	s_waitcnt vmcnt(19)
	v_lshlrev_b32_e32 v202, 16, v70
	v_and_b32_e32 v203, 0xffff0000, v70
	v_lshlrev_b32_e32 v200, 16, v71
	s_waitcnt vmcnt(16)
	v_and_b32_e32 v69, 0xffff0000, v86
	v_and_b32_e32 v209, 0xffff0000, v84
	v_and_b32_e32 v201, 0xffff0000, v71
	v_lshlrev_b32_e32 v68, 16, v86
	v_lshlrev_b32_e32 v70, 16, v85
	v_and_b32_e32 v71, 0xffff0000, v85
	v_lshlrev_b32_e32 v208, 16, v84
	v_mov_b32_e32 v84, v69
	v_mov_b32_e32 v85, v209
	v_lshlrev_b32_e32 v192, 16, v74
	v_and_b32_e32 v193, 0xffff0000, v74
	v_mul_f32_e32 v74, v71, v71
	v_mov_b32_e32 v78, v68
	v_mov_b32_e32 v79, v208
	v_pk_mul_f32 v[84:85], v[84:85], v[84:85]
	v_lshlrev_b32_e32 v194, 16, v75
	v_and_b32_e32 v195, 0xffff0000, v75
	v_pk_fma_f32 v[74:75], v[70:71], v[70:71], v[74:75] op_sel_hi:[1,1,0]
	v_pk_fma_f32 v[78:79], v[78:79], v[78:79], v[84:85]
	s_waitcnt vmcnt(15)
	v_and_b32_e32 v175, 0xffff0000, v52
	v_pk_add_f32 v[74:75], v[78:79], v[74:75] op_sel:[1,0] op_sel_hi:[0,1]
	v_and_b32_e32 v174, 0xffff0000, v72
	v_pk_add_f32 v[84:85], v[78:79], v[74:75]
	v_lshlrev_b32_e32 v179, 16, v52
	v_lshlrev_b32_e32 v178, 16, v72
	v_pk_mul_f32 v[74:75], v[174:175], v[174:175]
	v_lshlrev_b32_e32 v206, 16, v87
	v_and_b32_e32 v207, 0xffff0000, v87
	v_pk_fma_f32 v[86:87], v[178:179], v[178:179], v[74:75]
	v_pk_mov_b32 v[74:75], v[72:73], v[54:55] op_sel:[1,0]
	v_lshlrev_b32_e32 v185, 16, v54
	v_and_b32_e32 v177, 0xffff0000, v75
	v_and_b32_e32 v176, 0xffff0000, v74
	v_lshlrev_b32_e32 v184, 16, v73
	v_pk_mul_f32 v[72:73], v[176:177], v[176:177]
	s_waitcnt vmcnt(6)
	v_and_b32_e32 v165, 0xffff0000, v36
	v_and_b32_e32 v164, 0xffff0000, v76
	v_pk_fma_f32 v[214:215], v[184:185], v[184:185], v[72:73]
	v_lshlrev_b32_e32 v163, 16, v36
	v_lshlrev_b32_e32 v162, 16, v76
	v_pk_mul_f32 v[72:73], v[164:165], v[164:165]
	v_lshlrev_b32_e32 v159, 16, v38
	v_pk_fma_f32 v[94:95], v[162:163], v[162:163], v[72:73]
	v_pk_mov_b32 v[72:73], v[76:77], v[38:39] op_sel:[1,0]
	v_lshlrev_b32_e32 v158, 16, v77
	v_and_b32_e32 v161, 0xffff0000, v73
	v_and_b32_e32 v160, 0xffff0000, v72
	v_pk_mul_f32 v[72:73], v[160:161], v[160:161]
	v_and_b32_e32 v137, 0xffff0000, v130
	v_and_b32_e32 v136, 0xffff0000, v88
	v_and_b32_e32 v129, 0xffff0000, v131
	v_and_b32_e32 v128, 0xffff0000, v89
	v_pk_fma_f32 v[96:97], v[158:159], v[158:159], v[72:73]
	v_lshlrev_b32_e32 v135, 16, v130
	v_lshlrev_b32_e32 v134, 16, v88
	v_pk_mul_f32 v[72:73], v[136:137], v[136:137]
	v_lshlrev_b32_e32 v127, 16, v131
	v_lshlrev_b32_e32 v126, 16, v89
	v_pk_mul_f32 v[74:75], v[128:129], v[128:129]
	v_pk_fma_f32 v[72:73], v[134:135], v[134:135], v[72:73]
	v_pk_fma_f32 v[74:75], v[126:127], v[126:127], v[74:75]
	v_and_b32_e32 v143, 0xffff0000, v132
	v_and_b32_e32 v142, 0xffff0000, v90
	v_pk_add_f32 v[72:73], v[72:73], v[74:75]
	v_lshlrev_b32_e32 v141, 16, v132
	v_lshlrev_b32_e32 v140, 16, v90
	v_pk_mul_f32 v[74:75], v[142:143], v[142:143]
	v_lshlrev_b32_e32 v131, 16, v133
	v_pk_fma_f32 v[74:75], v[140:141], v[140:141], v[74:75]
	v_and_b32_e32 v133, 0xffff0000, v133
	v_and_b32_e32 v132, 0xffff0000, v91
	v_and_b32_e32 v139, 0xffff0000, v33
	v_and_b32_e32 v138, 0xffff0000, v32
	v_pk_add_f32 v[72:73], v[74:75], v[72:73]
	v_lshlrev_b32_e32 v130, 16, v91
	v_pk_mul_f32 v[74:75], v[132:133], v[132:133]
	v_lshlrev_b32_e32 v147, 16, v33
	v_lshlrev_b32_e32 v146, 16, v32
	v_pk_mul_f32 v[32:33], v[138:139], v[138:139]
	v_and_b32_e32 v145, 0xffff0000, v35
	v_and_b32_e32 v144, 0xffff0000, v34
	v_pk_fma_f32 v[74:75], v[130:131], v[130:131], v[74:75]
	s_waitcnt vmcnt(0)
	v_and_b32_e32 v191, 0xffff0000, v154
	v_and_b32_e32 v190, 0xffff0000, v150
	v_and_b32_e32 v183, 0xffff0000, v155
	v_and_b32_e32 v182, 0xffff0000, v151
	v_pk_fma_f32 v[32:33], v[146:147], v[146:147], v[32:33]
	v_lshlrev_b32_e32 v149, 16, v35
	v_lshlrev_b32_e32 v148, 16, v34
	v_pk_mul_f32 v[34:35], v[144:145], v[144:145]
	v_pk_add_f32 v[236:237], v[74:75], v[72:73]
	v_lshlrev_b32_e32 v189, 16, v154
	v_lshlrev_b32_e32 v188, 16, v150
	v_pk_mul_f32 v[72:73], v[190:191], v[190:191]
	v_lshlrev_b32_e32 v181, 16, v155
	v_lshlrev_b32_e32 v180, 16, v151
	v_pk_mul_f32 v[74:75], v[182:183], v[182:183]
	v_pk_add_f32 v[32:33], v[32:33], v[32:33] op_sel:[0,1] op_sel_hi:[1,0]
	v_pk_fma_f32 v[34:35], v[148:149], v[148:149], v[34:35]
	v_pk_fma_f32 v[72:73], v[188:189], v[188:189], v[72:73]
	v_pk_fma_f32 v[74:75], v[180:181], v[180:181], v[74:75]
	v_and_b32_e32 v199, 0xffff0000, v156
	v_and_b32_e32 v198, 0xffff0000, v152
	v_pk_add_f32 v[32:33], v[34:35], v[32:33]
	v_pk_add_f32 v[72:73], v[72:73], v[74:75]
	v_lshlrev_b32_e32 v197, 16, v156
	v_lshlrev_b32_e32 v196, 16, v152
	v_pk_mul_f32 v[74:75], v[198:199], v[198:199]
	v_mul_f32_e32 v40, v203, v203
	v_pk_add_f32 v[92:93], v[34:35], v[32:33] op_sel:[1,0] op_sel_hi:[0,1]
	v_mul_f32_e32 v32, v193, v193
	v_pk_fma_f32 v[74:75], v[196:197], v[196:197], v[74:75]
	v_and_b32_e32 v187, 0xffff0000, v157
	v_and_b32_e32 v186, 0xffff0000, v153
	v_pk_fma_f32 v[80:81], v[202:203], v[202:203], v[40:41] op_sel_hi:[1,1,0]
	v_mul_f32_e32 v40, v201, v201
	v_pk_fma_f32 v[64:65], v[192:193], v[192:193], v[32:33] op_sel_hi:[1,1,0]
	v_mul_f32_e32 v32, v195, v195
	v_pk_add_f32 v[72:73], v[74:75], v[72:73]
	v_lshlrev_b32_e32 v205, 16, v157
	v_lshlrev_b32_e32 v204, 16, v153
	v_pk_mul_f32 v[74:75], v[186:187], v[186:187]
	v_pk_fma_f32 v[82:83], v[200:201], v[200:201], v[40:41] op_sel_hi:[1,1,0]
	v_pk_fma_f32 v[66:67], v[194:195], v[194:195], v[32:33] op_sel_hi:[1,1,0]
	global_load_dwordx4 v[32:35], v101, s[46:47] offset:48
	global_load_dwordx4 v[40:43], v101, s[46:47] offset:32
	global_load_dwordx4 v[44:47], v101, s[46:47] offset:16
	global_load_dwordx4 v[48:51], v101, s[46:47]
	v_pk_fma_f32 v[74:75], v[204:205], v[204:205], v[74:75]
	v_and_b32_e32 v169, 0xffff0000, v60
	v_and_b32_e32 v168, 0xffff0000, v56
	v_and_b32_e32 v153, 0xffff0000, v61
	v_and_b32_e32 v152, 0xffff0000, v57
	v_pk_add_f32 v[238:239], v[74:75], v[72:73]
	v_lshlrev_b32_e32 v167, 16, v60
	v_lshlrev_b32_e32 v166, 16, v56
	v_pk_mul_f32 v[72:73], v[168:169], v[168:169]
	v_lshlrev_b32_e32 v151, 16, v61
	v_lshlrev_b32_e32 v150, 16, v57
	v_pk_mul_f32 v[56:57], v[152:153], v[152:153]
	v_and_b32_e32 v173, 0xffff0000, v62
	v_and_b32_e32 v172, 0xffff0000, v58
	v_pk_fma_f32 v[72:73], v[166:167], v[166:167], v[72:73]
	v_pk_fma_f32 v[56:57], v[150:151], v[150:151], v[56:57]
	v_lshlrev_b32_e32 v171, 16, v62
	v_lshlrev_b32_e32 v170, 16, v58
	v_pk_mul_f32 v[60:61], v[172:173], v[172:173]
	v_and_b32_e32 v157, 0xffff0000, v63
	v_and_b32_e32 v156, 0xffff0000, v59
	v_pk_add_f32 v[56:57], v[72:73], v[56:57]
	v_pk_fma_f32 v[60:61], v[170:171], v[170:171], v[60:61]
	v_lshlrev_b32_e32 v155, 16, v63
	v_lshlrev_b32_e32 v154, 16, v59
	v_pk_mul_f32 v[58:59], v[156:157], v[156:157]
	v_pk_add_f32 v[56:57], v[60:61], v[56:57]
	v_pk_fma_f32 v[58:59], v[154:155], v[154:155], v[58:59]
	v_mul_f32_e32 v98, v207, v207
	v_pk_add_f32 v[240:241], v[58:59], v[56:57]
	global_load_dwordx4 v[56:59], v101, s[46:47] offset:112
	global_load_dwordx4 v[60:63], v101, s[46:47] offset:96
	global_load_dwordx4 v[72:75], v101, s[46:47] offset:80
	global_load_dwordx4 v[76:79], v101, s[46:47] offset:64
	global_load_dwordx4 v[220:223], v101, s[46:47] offset:144
	global_load_dwordx4 v[224:227], v101, s[46:47] offset:128
	global_load_dwordx4 v[228:231], v101, s[46:47] offset:176
	global_load_dwordx4 v[232:235], v101, s[46:47] offset:160
	v_lshlrev_b32_e32 v210, 16, v55
	v_and_b32_e32 v55, 0xffff0000, v55
	v_lshlrev_b32_e32 v212, 16, v53
	v_and_b32_e32 v213, 0xffff0000, v53
	v_mov_b32_e32 v99, v98
	v_mov_b32_e32 v211, v55
	v_pk_mul_f32 v[52:53], v[212:213], v[212:213]
	v_and_b32_e32 v54, s0, v54
	v_pk_mov_b32 v[88:89], v[98:99], v[210:211] op_sel:[1,0]
	v_mov_b32_e32 v81, v52
	v_mov_b32_e32 v83, v53
	v_pk_mul_f32 v[54:55], v[54:55], v[54:55]
	v_pk_fma_f32 v[90:91], v[206:207], v[206:207], v[88:89]
	v_pk_mul_f32 v[88:89], v[210:211], v[88:89] op_sel_hi:[0,1]
	v_pk_add_f32 v[52:53], v[80:81], v[82:83]
	v_mov_b32_e32 v91, v89
	v_mov_b32_e32 v85, v55
	v_pk_add_f32 v[52:53], v[86:87], v[52:53]
	v_lshlrev_b32_e32 v216, 16, v37
	v_and_b32_e32 v217, 0xffff0000, v37
	v_pk_add_f32 v[54:55], v[90:91], v[84:85]
	v_pk_add_f32 v[52:53], v[214:215], v[52:53]
	v_pk_mul_f32 v[36:37], v[216:217], v[216:217]
	v_pk_add_f32 v[52:53], v[54:55], v[52:53]
	v_lshlrev_b32_e32 v214, 16, v39
	v_and_b32_e32 v215, 0xffff0000, v39
	v_mov_b32_e32 v65, v36
	v_mov_b32_e32 v67, v37
	v_pk_add_f32 v[98:99], v[52:53], v[52:53] op_sel:[0,1] op_sel_hi:[1,0]
	v_pk_mul_f32 v[38:39], v[214:215], v[214:215]
	v_pk_add_f32 v[36:37], v[64:65], v[66:67]
	v_mov_b32_e32 v93, v39
	v_mov_b32_e32 v99, v38
	v_pk_add_f32 v[36:37], v[94:95], v[36:37]
	v_pk_add_f32 v[38:39], v[98:99], v[92:93]
	v_pk_add_f32 v[36:37], v[96:97], v[36:37]
	v_mov_b32_e32 v246, v162
	v_pk_add_f32 v[36:37], v[38:39], v[36:37]
	v_mov_b32_e32 v242, v178
	v_pk_add_f32 v[36:37], v[36:37], v[236:237]
	v_mov_b32_e32 v243, v174
	v_pk_add_f32 v[36:37], v[36:37], v[238:239]
	v_mov_b32_e32 v244, v184
	v_pk_add_f32 v[36:37], v[36:37], v[240:241]
	v_mov_b32_e32 v245, v176
	v_fmac_f32_e32 v37, v111, v36
	v_fmamk_f32 v36, v37, 0x3c2aaaab, v100
	v_mul_f32_e32 v37, 0x4b800000, v36
	v_cmp_gt_f32_e32 vcc, s19, v36
	global_load_dwordx4 v[52:55], v101, s[46:47] offset:240
	global_load_dwordx4 v[80:83], v101, s[46:47] offset:224
	global_load_dwordx4 v[84:87], v101, s[46:47] offset:208
	global_load_dwordx4 v[88:91], v101, s[46:47] offset:192
	v_cndmask_b32_e32 v36, v36, v37, vcc
	v_rsq_f32_e32 v111, v36
	global_load_dwordx4 v[36:39], v101, s[46:47] offset:304
	global_load_dwordx4 v[64:67], v101, s[46:47] offset:288
	global_load_dwordx4 v[96:99], v101, s[46:47] offset:256
	global_load_dwordx4 v[92:95], v101, s[46:47] offset:272
	v_mov_b32_e32 v247, v164
	v_mov_b32_e32 v240, v126
	v_mul_f32_e32 v123, 0x45800000, v111
	v_cndmask_b32_e32 v162, v111, v123, vcc
	v_mul_f32_e32 v178, v122, v162
	s_waitcnt vmcnt(18)
	v_pk_mul_f32 v[40:41], v[40:41], v[178:179] op_sel_hi:[1,0]
	v_pk_mul_f32 v[32:33], v[32:33], v[178:179] op_sel_hi:[1,0]
	v_pk_mul_f32 v[40:41], v[40:41], v[202:203]
	v_pk_mul_f32 v[202:203], v[32:33], v[242:243]
	v_pk_mul_f32 v[32:33], v[42:43], v[178:179] op_sel_hi:[1,0]
	s_waitcnt vmcnt(16)
	v_pk_mul_f32 v[48:49], v[48:49], v[178:179] op_sel_hi:[1,0]
	v_pk_mul_f32 v[200:201], v[32:33], v[200:201]
	v_pk_mul_f32 v[32:33], v[34:35], v[178:179] op_sel_hi:[1,0]
	v_pk_mul_f32 v[208:209], v[48:49], v[208:209]
	v_pk_mul_f32 v[44:45], v[44:45], v[178:179] op_sel_hi:[1,0]
	v_pk_mul_f32 v[48:49], v[50:51], v[178:179] op_sel_hi:[1,0]
	v_pk_mul_f32 v[46:47], v[46:47], v[178:179] op_sel_hi:[1,0]
	v_pk_mul_f32 v[244:245], v[32:33], v[244:245]
	v_pk_mul_f32 v[44:45], v[44:45], v[68:69]
	v_pk_mul_f32 v[236:237], v[48:49], v[70:71]
	v_pk_mul_f32 v[46:47], v[46:47], v[206:207]
	v_cvt_pk_bf16_f32 v32, v40, v41
	v_cvt_pk_bf16_f32 v33, v200, v201
	v_cvt_pk_bf16_f32 v34, v202, v203
	v_cvt_pk_bf16_f32 v35, v244, v245
	global_load_dwordx4 v[48:51], v101, s[46:47] offset:368
	global_load_dwordx4 v[68:71], v101, s[46:47] offset:352
	v_cvt_pk_bf16_f32 v206, v208, v209
	v_cvt_pk_bf16_f32 v207, v236, v237
	v_cvt_pk_bf16_f32 v208, v44, v45
	v_cvt_pk_bf16_f32 v209, v46, v47
	global_load_dwordx4 v[236:239], v101, s[46:47] offset:320
	global_load_dwordx4 v[44:47], v101, s[46:47] offset:336
	s_waitcnt vmcnt(14)
	v_pk_mul_f32 v[40:41], v[226:227], v[178:179] op_sel_hi:[1,0]
	s_mul_i32 s57, s33, 0xc0
	v_mbcnt_lo_u32_b32 v244, -1, 0
	v_mbcnt_hi_u32_b32 v244, -1, v244
	v_mul_u32_u24_e32 v244, 0xc0, v244
	v_add_u32_e32 v244, s57, v244
	ds_write_b128 v244, v[32:35] offset:16
	ds_write_b128 v244, v[206:209]
	v_pk_mul_f32 v[40:41], v[40:41], v[194:195]
	v_pk_mul_f32 v[32:33], v[224:225], v[178:179] op_sel_hi:[1,0]
	v_mov_b32_e32 v206, v158
	v_mov_b32_e32 v207, v160
	v_pk_mul_f32 v[32:33], v[32:33], v[192:193]
	v_pk_mul_f32 v[34:35], v[220:221], v[178:179] op_sel_hi:[1,0]
	v_pk_mul_f32 v[192:193], v[222:223], v[178:179] op_sel_hi:[1,0]
	v_pk_mul_f32 v[34:35], v[34:35], v[246:247]
	v_pk_mul_f32 v[192:193], v[192:193], v[206:207]
	v_cvt_pk_bf16_f32 v32, v32, v33
	v_cvt_pk_bf16_f32 v33, v40, v41
	v_cvt_pk_bf16_f32 v34, v34, v35
	v_cvt_pk_bf16_f32 v35, v192, v193
	v_mov_b32_e32 v42, v140
	v_mov_b32_e32 v43, v142
	ds_write_b128 v244, v[32:35] offset:64
	v_mov_b32_e32 v208, v134
	v_mov_b32_e32 v209, v136
	s_waitcnt vmcnt(13)
	v_pk_mul_f32 v[34:35], v[178:179], v[228:229] op_sel_hi:[0,1]
	v_mov_b32_e32 v241, v128
	v_mov_b32_e32 v242, v130
	v_mov_b32_e32 v243, v132
	s_waitcnt vmcnt(12)
	v_pk_mul_f32 v[32:33], v[178:179], v[232:233] op_sel_hi:[0,1]
	v_pk_mul_f32 v[34:35], v[34:35], v[42:43]
	v_pk_mul_f32 v[40:41], v[178:179], v[234:235] op_sel_hi:[0,1]
	v_pk_mul_f32 v[42:43], v[178:179], v[230:231] op_sel_hi:[0,1]
	v_pk_mul_f32 v[32:33], v[32:33], v[208:209]
	v_pk_mul_f32 v[40:41], v[40:41], v[240:241]
	v_pk_mul_f32 v[42:43], v[42:43], v[242:243]
	v_cvt_pk_bf16_f32 v32, v32, v33
	v_cvt_pk_bf16_f32 v33, v40, v41
	v_cvt_pk_bf16_f32 v34, v34, v35
	v_cvt_pk_bf16_f32 v35, v42, v43
	global_load_dwordx4 v[40:43], v[120:121], off
	global_load_dwordx4 v[192:195], v[118:119], off
	v_mov_b32_e32 v176, v185
	ds_write_b128 v244, v[32:35] offset:80
	global_load_dwordx4 v[32:35], v[118:119], off offset:16
	s_nop 0
	global_load_dwordx4 v[200:203], v[120:121], off offset:16
	v_mov_b32_e32 v174, v179
	v_pk_mul_f32 v[76:77], v[76:77], v[178:179] op_sel_hi:[1,0]
	v_pk_mul_f32 v[72:73], v[72:73], v[178:179] op_sel_hi:[1,0]
	v_pk_mul_f32 v[76:77], v[76:77], v[174:175]
	v_pk_mul_f32 v[174:175], v[72:73], v[176:177]
	v_pk_mul_f32 v[72:73], v[78:79], v[178:179] op_sel_hi:[1,0]
	v_mov_b32_e32 v206, v148
	v_pk_mul_f32 v[78:79], v[72:73], v[212:213]
	v_pk_mul_f32 v[72:73], v[74:75], v[178:179] op_sel_hi:[1,0]
	v_mov_b32_e32 v207, v144
	v_pk_mul_f32 v[176:177], v[72:73], v[210:211]
	v_cvt_pk_bf16_f32 v72, v76, v77
	v_cvt_pk_bf16_f32 v73, v78, v79
	v_cvt_pk_bf16_f32 v74, v174, v175
	v_cvt_pk_bf16_f32 v75, v176, v177
	v_pk_mul_f32 v[56:57], v[56:57], v[178:179] op_sel_hi:[1,0]
	v_mov_b32_e32 v185, v138
	v_mov_b32_e32 v138, v147
	ds_write_b128 v244, v[72:75] offset:32
	v_mov_b32_e32 v184, v146
	v_mov_b32_e32 v144, v149
	v_pk_mul_f32 v[72:73], v[56:57], v[206:207]
	v_pk_mul_f32 v[56:57], v[62:63], v[178:179] op_sel_hi:[1,0]
	v_pk_mul_f32 v[60:61], v[60:61], v[178:179] op_sel_hi:[1,0]
	v_pk_mul_f32 v[62:63], v[56:57], v[138:139]
	v_pk_mul_f32 v[56:57], v[58:59], v[178:179] op_sel_hi:[1,0]
	v_pk_mul_f32 v[60:61], v[60:61], v[184:185]
	v_pk_mul_f32 v[74:75], v[56:57], v[144:145]
	v_cvt_pk_bf16_f32 v56, v60, v61
	v_cvt_pk_bf16_f32 v57, v62, v63
	v_cvt_pk_bf16_f32 v58, v72, v73
	v_cvt_pk_bf16_f32 v59, v74, v75
	v_mov_b32_e32 v146, v188
	v_mov_b32_e32 v147, v190
	v_mov_b32_e32 v148, v196
	v_mov_b32_e32 v149, v198
	v_mov_b32_e32 v208, v180
	v_mov_b32_e32 v209, v182
	v_mov_b32_e32 v220, v204
	v_mov_b32_e32 v221, v186
	ds_write_b128 v244, v[56:59] offset:48
	s_waitcnt vmcnt(12)
	v_pk_mul_f32 v[60:61], v[178:179], v[90:91] op_sel_hi:[0,1]
	v_pk_mul_f32 v[62:63], v[178:179], v[86:87] op_sel_hi:[0,1]
	v_pk_mul_f32 v[56:57], v[178:179], v[88:89] op_sel_hi:[0,1]
	v_pk_mul_f32 v[58:59], v[178:179], v[84:85] op_sel_hi:[0,1]
	v_pk_mul_f32 v[56:57], v[56:57], v[146:147]
	v_pk_mul_f32 v[58:59], v[58:59], v[148:149]
	v_pk_mul_f32 v[60:61], v[60:61], v[208:209]
	v_pk_mul_f32 v[62:63], v[62:63], v[220:221]
	v_cvt_pk_bf16_f32 v56, v56, v57
	v_cvt_pk_bf16_f32 v57, v60, v61
	v_cvt_pk_bf16_f32 v58, v58, v59
	v_cvt_pk_bf16_f32 v59, v62, v63
	v_mov_b32_e32 v198, v197
	ds_write_b128 v244, v[56:59] offset:96
	v_mov_b32_e32 v160, v159
	v_mov_b32_e32 v182, v181
	v_pk_mul_f32 v[58:59], v[162:163], v[198:199] op_sel_hi:[0,1]
	s_waitcnt vmcnt(4)
	v_pk_mul_f32 v[76:77], v[58:59], v[44:45]
	v_pk_mul_f32 v[44:45], v[162:163], v[160:161] op_sel_hi:[0,1]
	v_pk_mul_f32 v[78:79], v[44:45], v[92:93]
	v_mov_b32_e32 v224, v170
	v_mov_b32_e32 v225, v172
	v_pk_mul_f32 v[56:57], v[178:179], v[80:81] op_sel_hi:[0,1]
	v_pk_mul_f32 v[52:53], v[178:179], v[52:53] op_sel_hi:[0,1]
	v_mov_b32_e32 v222, v166
	v_mov_b32_e32 v223, v168
	v_pk_mul_f32 v[62:63], v[52:53], v[224:225]
	v_pk_mul_f32 v[52:53], v[178:179], v[82:83] op_sel_hi:[0,1]
	v_mov_b32_e32 v164, v163
	v_mov_b32_e32 v186, v205
	v_pk_mul_f32 v[60:61], v[56:57], v[222:223]
	v_pk_mul_f32 v[56:57], v[162:163], v[164:165] op_sel_hi:[0,1]
	v_mov_b32_e32 v190, v189
	v_pk_mul_f32 v[72:73], v[56:57], v[96:97]
	v_pk_mul_f32 v[56:57], v[162:163], v[190:191] op_sel_hi:[0,1]
	v_pk_mul_f32 v[74:75], v[56:57], v[236:237]
	s_waitcnt vmcnt(3)
	v_pk_mul_f32 v[56:57], v[72:73], v[40:41]
	v_mov_b32_e32 v226, v150
	s_waitcnt vmcnt(0)
	v_pk_mul_f32 v[44:45], v[78:79], v[200:201]
	v_pk_fma_f32 v[56:57], v[74:75], v[192:193], v[56:57]
	v_pk_fma_f32 v[58:59], v[76:77], v[32:33], v[44:45]
	v_pk_mul_f32 v[44:45], v[162:163], v[216:217] op_sel_hi:[0,1]
	v_pk_mul_f32 v[80:81], v[44:45], v[98:99]
	v_pk_mul_f32 v[44:45], v[162:163], v[182:183] op_sel_hi:[0,1]
	v_pk_mul_f32 v[82:83], v[44:45], v[238:239]
	v_pk_mul_f32 v[44:45], v[80:81], v[42:43]
	v_mov_b32_e32 v227, v152
	v_pk_fma_f32 v[84:85], v[82:83], v[194:195], v[44:45]
	v_pk_mul_f32 v[44:45], v[162:163], v[214:215] op_sel_hi:[0,1]
	v_pk_mul_f32 v[86:87], v[44:45], v[94:95]
	v_pk_mul_f32 v[44:45], v[162:163], v[186:187] op_sel_hi:[0,1]
	v_pk_mul_f32 v[88:89], v[44:45], v[46:47]
	v_pk_mul_f32 v[44:45], v[86:87], v[202:203]
	v_cvt_pk_bf16_f32 v46, v58, v59
	v_pk_fma_f32 v[90:91], v[88:89], v[34:35], v[44:45]
	v_cvt_pk_bf16_f32 v44, v56, v57
	v_cvt_pk_bf16_f32 v45, v84, v85
	v_cvt_pk_bf16_f32 v47, v90, v91
	ds_write_b128 v244, v[44:47] offset:160
	v_mov_b32_e32 v228, v154
	v_mov_b32_e32 v229, v156
	global_load_dwordx4 v[44:47], v[120:121], off offset:32
	global_load_dwordx4 v[56:59], v[118:119], off offset:32
	v_pk_mul_f32 v[84:85], v[52:53], v[226:227]
	v_pk_mul_f32 v[52:53], v[178:179], v[54:55] op_sel_hi:[0,1]
	v_pk_mul_f32 v[90:91], v[52:53], v[228:229]
	v_cvt_pk_bf16_f32 v52, v60, v61
	v_cvt_pk_bf16_f32 v53, v84, v85
	v_cvt_pk_bf16_f32 v54, v62, v63
	v_cvt_pk_bf16_f32 v55, v90, v91
	ds_write_b128 v244, v[52:55] offset:112
	global_load_dwordx4 v[52:55], v[120:121], off offset:48
	s_nop 0
	global_load_dwordx4 v[60:63], v[118:119], off offset:48
	v_pk_mul_f32 v[40:41], v[74:75], v[40:41]
	v_mov_b32_e32 v136, v135
	v_pk_fma_f32 v[40:41], v[72:73], v[192:193], v[40:41] neg_lo:[0,0,1] neg_hi:[0,0,1]
	v_pk_mul_f32 v[72:73], v[76:77], v[200:201]
	v_mov_b32_e32 v168, v167
	v_pk_fma_f32 v[72:73], v[78:79], v[32:33], v[72:73] neg_lo:[0,0,1] neg_hi:[0,0,1]
	v_pk_mul_f32 v[32:33], v[82:83], v[42:43]
	v_mov_b32_e32 v172, v171
	v_pk_fma_f32 v[42:43], v[80:81], v[194:195], v[32:33] neg_lo:[0,0,1] neg_hi:[0,0,1]
	v_pk_mul_f32 v[32:33], v[88:89], v[202:203]
	v_mov_b32_e32 v142, v141
	v_pk_fma_f32 v[74:75], v[86:87], v[34:35], v[32:33] neg_lo:[0,0,1] neg_hi:[0,0,1]
	v_cvt_pk_bf16_f32 v32, v40, v41
	v_cvt_pk_bf16_f32 v33, v42, v43
	v_cvt_pk_bf16_f32 v34, v72, v73
	v_cvt_pk_bf16_f32 v35, v74, v75
	ds_write_b128 v244, v[32:35] offset:128
	v_pk_mul_f32 v[42:43], v[162:163], v[142:143] op_sel_hi:[0,1]
	v_pk_mul_f32 v[36:37], v[42:43], v[36:37]
	v_pk_mul_f32 v[32:33], v[162:163], v[136:137] op_sel_hi:[0,1]
	v_pk_mul_f32 v[32:33], v[32:33], v[64:65]
	v_pk_mul_f32 v[34:35], v[162:163], v[168:169] op_sel_hi:[0,1]
	v_pk_mul_f32 v[34:35], v[34:35], v[68:69]
	v_mov_b32_e32 v128, v127
	v_mov_b32_e32 v152, v151
	v_mov_b32_e32 v132, v131
	v_mov_b32_e32 v156, v155
	s_waitcnt vmcnt(3)
	v_pk_mul_f32 v[40:41], v[32:33], v[44:45]
	s_waitcnt vmcnt(2)
	v_pk_fma_f32 v[40:41], v[34:35], v[56:57], v[40:41]
	v_pk_mul_f32 v[34:35], v[34:35], v[44:45]
	v_pk_mul_f32 v[44:45], v[162:163], v[152:153] op_sel_hi:[0,1]
	v_pk_fma_f32 v[32:33], v[32:33], v[56:57], v[34:35] neg_lo:[0,0,1] neg_hi:[0,0,1]
	v_pk_mul_f32 v[34:35], v[162:163], v[172:173] op_sel_hi:[0,1]
	v_pk_mul_f32 v[34:35], v[34:35], v[48:49]
	v_pk_mul_f32 v[44:45], v[44:45], v[70:71]
	v_cvt_pk_bf16_f32 v32, v32, v33
	s_waitcnt vmcnt(1)
	v_pk_mul_f32 v[42:43], v[34:35], v[52:53]
	s_waitcnt vmcnt(0)
	v_pk_fma_f32 v[42:43], v[36:37], v[60:61], v[42:43] neg_lo:[0,0,1] neg_hi:[0,0,1]
	v_pk_mul_f32 v[36:37], v[36:37], v[52:53]
	s_nop 0
	v_pk_fma_f32 v[36:37], v[34:35], v[60:61], v[36:37]
	v_pk_mul_f32 v[34:35], v[162:163], v[128:129] op_sel_hi:[0,1]
	v_pk_mul_f32 v[34:35], v[34:35], v[66:67]
	s_nop 0
	v_pk_mul_f32 v[48:49], v[34:35], v[46:47]
	s_nop 0
	v_pk_fma_f32 v[48:49], v[44:45], v[58:59], v[48:49]
	v_pk_mul_f32 v[44:45], v[44:45], v[46:47]
	s_nop 0
	v_pk_fma_f32 v[34:35], v[34:35], v[58:59], v[44:45] neg_lo:[0,0,1] neg_hi:[0,0,1]
	v_pk_mul_f32 v[44:45], v[162:163], v[132:133] op_sel_hi:[0,1]
	v_pk_mul_f32 v[38:39], v[44:45], v[38:39]
	v_pk_mul_f32 v[44:45], v[162:163], v[156:157] op_sel_hi:[0,1]
	v_pk_mul_f32 v[44:45], v[44:45], v[50:51]
	v_pk_mul_f32 v[46:47], v[38:39], v[54:55]
	v_cvt_pk_bf16_f32 v33, v34, v35
	v_pk_fma_f32 v[46:47], v[44:45], v[62:63], v[46:47]
	v_pk_mul_f32 v[44:45], v[44:45], v[54:55]
	v_cvt_pk_bf16_f32 v34, v42, v43
	v_pk_fma_f32 v[38:39], v[38:39], v[62:63], v[44:45] neg_lo:[0,0,1] neg_hi:[0,0,1]
	s_nop 0
	v_cvt_pk_bf16_f32 v35, v38, v39
	ds_write_b128 v244, v[32:35] offset:144
	s_nop 1
	v_cvt_pk_bf16_f32 v32, v40, v41
	v_cvt_pk_bf16_f32 v33, v48, v49
	v_cvt_pk_bf16_f32 v34, v36, v37
	v_cvt_pk_bf16_f32 v35, v46, v47
	ds_write_b128 v244, v[32:35] offset:176
	v_readfirstlane_b32 s60, v124
	v_readfirstlane_b32 s61, v125
	v_mbcnt_lo_u32_b32 v42, -1, 0
	v_mbcnt_hi_u32_b32 v42, -1, v42
	v_mov_b32_e32 v43, v42
	v_mul_u32_u24_e32 v44, 0xaaab, v43
	v_lshrrev_b32_e32 v44, 22, v44
	v_mul_u32_u24_e32 v45, 0x60, v44
	v_sub_u32_e32 v45, v43, v45
	v_mul_u32_u24_e32 v46, 0x1556, v45
	v_lshrrev_b32_e32 v46, 16, v46
	v_mul_u32_u24_e32 v47, 12, v46
	v_sub_u32_e32 v47, v45, v47
	v_lshl_add_u32 v48, v46, 3, v44
	v_mul_u32_u24_e32 v48, 0xc0, v48
	v_lshl_add_u32 v48, v47, 4, v48
	v_add_u32_e32 v48, s57, v48
	ds_read_b128 v[60:63], v48
	v_mul_u32_u24_e32 v52, 0x180000, v44
	v_lshl_add_u32 v52, v45, 4, v52
	v_add_u32_e32 v43, 0x40, v42
	v_mul_u32_u24_e32 v44, 0xaaab, v43
	v_lshrrev_b32_e32 v44, 22, v44
	v_mul_u32_u24_e32 v45, 0x60, v44
	v_sub_u32_e32 v45, v43, v45
	v_mul_u32_u24_e32 v46, 0x1556, v45
	v_lshrrev_b32_e32 v46, 16, v46
	v_mul_u32_u24_e32 v47, 12, v46
	v_sub_u32_e32 v47, v45, v47
	v_lshl_add_u32 v49, v46, 3, v44
	v_mul_u32_u24_e32 v49, 0xc0, v49
	v_lshl_add_u32 v49, v47, 4, v49
	v_add_u32_e32 v49, s57, v49
	ds_read_b128 v[64:67], v49
	v_mul_u32_u24_e32 v53, 0x180000, v44
	v_lshl_add_u32 v53, v45, 4, v53
	v_add_u32_e32 v43, 0x80, v42
	v_mul_u32_u24_e32 v44, 0xaaab, v43
	v_lshrrev_b32_e32 v44, 22, v44
	v_mul_u32_u24_e32 v45, 0x60, v44
	v_sub_u32_e32 v45, v43, v45
	v_mul_u32_u24_e32 v46, 0x1556, v45
	v_lshrrev_b32_e32 v46, 16, v46
	v_mul_u32_u24_e32 v47, 12, v46
	v_sub_u32_e32 v47, v45, v47
	v_lshl_add_u32 v50, v46, 3, v44
	v_mul_u32_u24_e32 v50, 0xc0, v50
	v_lshl_add_u32 v50, v47, 4, v50
	v_add_u32_e32 v50, s57, v50
	ds_read_b128 v[68:71], v50
	v_mul_u32_u24_e32 v54, 0x180000, v44
	v_lshl_add_u32 v54, v45, 4, v54
	v_add_u32_e32 v43, 0xc0, v42
	v_mul_u32_u24_e32 v44, 0xaaab, v43
	v_lshrrev_b32_e32 v44, 22, v44
	v_mul_u32_u24_e32 v45, 0x60, v44
	v_sub_u32_e32 v45, v43, v45
	v_mul_u32_u24_e32 v46, 0x1556, v45
	v_lshrrev_b32_e32 v46, 16, v46
	v_mul_u32_u24_e32 v47, 12, v46
	v_sub_u32_e32 v47, v45, v47
	v_lshl_add_u32 v51, v46, 3, v44
	v_mul_u32_u24_e32 v51, 0xc0, v51
	v_lshl_add_u32 v51, v47, 4, v51
	v_add_u32_e32 v51, s57, v51
	ds_read_b128 v[72:75], v51
	v_mul_u32_u24_e32 v55, 0x180000, v44
	v_lshl_add_u32 v55, v45, 4, v55
	s_waitcnt lgkmcnt(0)
	global_store_dwordx4 v52, v[60:63], s[60:61]
	global_store_dwordx4 v53, v[64:67], s[60:61]
	global_store_dwordx4 v54, v[68:71], s[60:61]
	global_store_dwordx4 v55, v[72:75], s[60:61]
	v_add_u32_e32 v43, 0x100, v42
	v_mul_u32_u24_e32 v44, 0xaaab, v43
	v_lshrrev_b32_e32 v44, 22, v44
	v_mul_u32_u24_e32 v45, 0x60, v44
	v_sub_u32_e32 v45, v43, v45
	v_mul_u32_u24_e32 v46, 0x1556, v45
	v_lshrrev_b32_e32 v46, 16, v46
	v_mul_u32_u24_e32 v47, 12, v46
	v_sub_u32_e32 v47, v45, v47
	v_lshl_add_u32 v48, v46, 3, v44
	v_mul_u32_u24_e32 v48, 0xc0, v48
	v_lshl_add_u32 v48, v47, 4, v48
	v_add_u32_e32 v48, s57, v48
	ds_read_b128 v[60:63], v48
	v_mul_u32_u24_e32 v52, 0x180000, v44
	v_lshl_add_u32 v52, v45, 4, v52
	v_add_u32_e32 v43, 0x140, v42
	v_mul_u32_u24_e32 v44, 0xaaab, v43
	v_lshrrev_b32_e32 v44, 22, v44
	v_mul_u32_u24_e32 v45, 0x60, v44
	v_sub_u32_e32 v45, v43, v45
	v_mul_u32_u24_e32 v46, 0x1556, v45
	v_lshrrev_b32_e32 v46, 16, v46
	v_mul_u32_u24_e32 v47, 12, v46
	v_sub_u32_e32 v47, v45, v47
	v_lshl_add_u32 v49, v46, 3, v44
	v_mul_u32_u24_e32 v49, 0xc0, v49
	v_lshl_add_u32 v49, v47, 4, v49
	v_add_u32_e32 v49, s57, v49
	ds_read_b128 v[64:67], v49
	v_mul_u32_u24_e32 v53, 0x180000, v44
	v_lshl_add_u32 v53, v45, 4, v53
	v_add_u32_e32 v43, 0x180, v42
	v_mul_u32_u24_e32 v44, 0xaaab, v43
	v_lshrrev_b32_e32 v44, 22, v44
	v_mul_u32_u24_e32 v45, 0x60, v44
	v_sub_u32_e32 v45, v43, v45
	v_mul_u32_u24_e32 v46, 0x1556, v45
	v_lshrrev_b32_e32 v46, 16, v46
	v_mul_u32_u24_e32 v47, 12, v46
	v_sub_u32_e32 v47, v45, v47
	v_lshl_add_u32 v50, v46, 3, v44
	v_mul_u32_u24_e32 v50, 0xc0, v50
	v_lshl_add_u32 v50, v47, 4, v50
	v_add_u32_e32 v50, s57, v50
	ds_read_b128 v[68:71], v50
	v_mul_u32_u24_e32 v54, 0x180000, v44
	v_lshl_add_u32 v54, v45, 4, v54
	v_add_u32_e32 v43, 0x1c0, v42
	v_mul_u32_u24_e32 v44, 0xaaab, v43
	v_lshrrev_b32_e32 v44, 22, v44
	v_mul_u32_u24_e32 v45, 0x60, v44
	v_sub_u32_e32 v45, v43, v45
	v_mul_u32_u24_e32 v46, 0x1556, v45
	v_lshrrev_b32_e32 v46, 16, v46
	v_mul_u32_u24_e32 v47, 12, v46
	v_sub_u32_e32 v47, v45, v47
	v_lshl_add_u32 v51, v46, 3, v44
	v_mul_u32_u24_e32 v51, 0xc0, v51
	v_lshl_add_u32 v51, v47, 4, v51
	v_add_u32_e32 v51, s57, v51
	ds_read_b128 v[72:75], v51
	v_mul_u32_u24_e32 v55, 0x180000, v44
	v_lshl_add_u32 v55, v45, 4, v55
	s_waitcnt lgkmcnt(0)
	global_store_dwordx4 v52, v[60:63], s[60:61]
	global_store_dwordx4 v53, v[64:67], s[60:61]
	global_store_dwordx4 v54, v[68:71], s[60:61]
	global_store_dwordx4 v55, v[72:75], s[60:61]
	v_add_u32_e32 v43, 0x200, v42
	v_mul_u32_u24_e32 v44, 0xaaab, v43
	v_lshrrev_b32_e32 v44, 22, v44
	v_mul_u32_u24_e32 v45, 0x60, v44
	v_sub_u32_e32 v45, v43, v45
	v_mul_u32_u24_e32 v46, 0x1556, v45
	v_lshrrev_b32_e32 v46, 16, v46
	v_mul_u32_u24_e32 v47, 12, v46
	v_sub_u32_e32 v47, v45, v47
	v_lshl_add_u32 v48, v46, 3, v44
	v_mul_u32_u24_e32 v48, 0xc0, v48
	v_lshl_add_u32 v48, v47, 4, v48
	v_add_u32_e32 v48, s57, v48
	ds_read_b128 v[60:63], v48
	v_mul_u32_u24_e32 v52, 0x180000, v44
	v_lshl_add_u32 v52, v45, 4, v52
	v_add_u32_e32 v43, 0x240, v42
	v_mul_u32_u24_e32 v44, 0xaaab, v43
	v_lshrrev_b32_e32 v44, 22, v44
	v_mul_u32_u24_e32 v45, 0x60, v44
	v_sub_u32_e32 v45, v43, v45
	v_mul_u32_u24_e32 v46, 0x1556, v45
	v_lshrrev_b32_e32 v46, 16, v46
	v_mul_u32_u24_e32 v47, 12, v46
	v_sub_u32_e32 v47, v45, v47
	v_lshl_add_u32 v49, v46, 3, v44
	v_mul_u32_u24_e32 v49, 0xc0, v49
	v_lshl_add_u32 v49, v47, 4, v49
	v_add_u32_e32 v49, s57, v49
	ds_read_b128 v[64:67], v49
	v_mul_u32_u24_e32 v53, 0x180000, v44
	v_lshl_add_u32 v53, v45, 4, v53
	v_add_u32_e32 v43, 0x280, v42
	v_mul_u32_u24_e32 v44, 0xaaab, v43
	v_lshrrev_b32_e32 v44, 22, v44
	v_mul_u32_u24_e32 v45, 0x60, v44
	v_sub_u32_e32 v45, v43, v45
	v_mul_u32_u24_e32 v46, 0x1556, v45
	v_lshrrev_b32_e32 v46, 16, v46
	v_mul_u32_u24_e32 v47, 12, v46
	v_sub_u32_e32 v47, v45, v47
	v_lshl_add_u32 v50, v46, 3, v44
	v_mul_u32_u24_e32 v50, 0xc0, v50
	v_lshl_add_u32 v50, v47, 4, v50
	v_add_u32_e32 v50, s57, v50
	ds_read_b128 v[68:71], v50
	v_mul_u32_u24_e32 v54, 0x180000, v44
	v_lshl_add_u32 v54, v45, 4, v54
	v_add_u32_e32 v43, 0x2c0, v42
	v_mul_u32_u24_e32 v44, 0xaaab, v43
	v_lshrrev_b32_e32 v44, 22, v44
	v_mul_u32_u24_e32 v45, 0x60, v44
	v_sub_u32_e32 v45, v43, v45
	v_mul_u32_u24_e32 v46, 0x1556, v45
	v_lshrrev_b32_e32 v46, 16, v46
	v_mul_u32_u24_e32 v47, 12, v46
	v_sub_u32_e32 v47, v45, v47
	v_lshl_add_u32 v51, v46, 3, v44
	v_mul_u32_u24_e32 v51, 0xc0, v51
	v_lshl_add_u32 v51, v47, 4, v51
	v_add_u32_e32 v51, s57, v51
	ds_read_b128 v[72:75], v51
	v_mul_u32_u24_e32 v55, 0x180000, v44
	v_lshl_add_u32 v55, v45, 4, v55
	s_waitcnt lgkmcnt(0)
	global_store_dwordx4 v52, v[60:63], s[60:61]
	global_store_dwordx4 v53, v[64:67], s[60:61]
	global_store_dwordx4 v54, v[68:71], s[60:61]
	global_store_dwordx4 v55, v[72:75], s[60:61]
	s_nop 1
	v_lshlrev_b32_e32 v34, 16, v28
	v_and_b32_e32 v35, 0xffff0000, v28
	v_lshlrev_b32_e32 v28, 16, v29
	v_and_b32_e32 v29, 0xffff0000, v29
	v_pk_mul_f32 v[36:37], v[122:123], v[28:29] op_sel_hi:[0,1]
	v_lshlrev_b32_e32 v28, 16, v30
	v_and_b32_e32 v29, 0xffff0000, v30
	v_pk_mul_f32 v[38:39], v[122:123], v[28:29] op_sel_hi:[0,1]
	v_lshlrev_b32_e32 v28, 16, v31
	v_and_b32_e32 v29, 0xffff0000, v31
	v_lshlrev_b64 v[32:33], 7, v[116:117]
	v_pk_mul_f32 v[34:35], v[122:123], v[34:35] op_sel_hi:[0,1]
	v_pk_mul_f32 v[40:41], v[122:123], v[28:29] op_sel_hi:[0,1]
	v_lshl_add_u64 v[32:33], s[12:13], 0, v[32:33]
	v_cvt_pk_bf16_f32 v28, v34, v35
	v_cvt_pk_bf16_f32 v29, v36, v37
	v_cvt_pk_bf16_f32 v30, v38, v39
	v_cvt_pk_bf16_f32 v31, v40, v41
	s_mul_i32 s57, s33, 0xc0
	v_mbcnt_lo_u32_b32 v38, -1, 0
	v_mbcnt_hi_u32_b32 v38, -1, v38
	v_mul_u32_u24_e32 v38, 0x80, v38
	v_add_u32_e32 v38, s57, v38
	ds_write_b128 v38, v[28:31]
	s_nop 1
	v_lshlrev_b32_e32 v28, 16, v24
	v_and_b32_e32 v29, 0xffff0000, v24
	v_lshlrev_b32_e32 v24, 16, v25
	v_and_b32_e32 v25, 0xffff0000, v25
	v_pk_mul_f32 v[30:31], v[122:123], v[24:25] op_sel_hi:[0,1]
	v_lshlrev_b32_e32 v24, 16, v26
	v_and_b32_e32 v25, 0xffff0000, v26
	v_pk_mul_f32 v[34:35], v[122:123], v[24:25] op_sel_hi:[0,1]
	v_lshlrev_b32_e32 v24, 16, v27
	v_and_b32_e32 v25, 0xffff0000, v27
	v_pk_mul_f32 v[28:29], v[122:123], v[28:29] op_sel_hi:[0,1]
	v_pk_mul_f32 v[36:37], v[122:123], v[24:25] op_sel_hi:[0,1]
	v_cvt_pk_bf16_f32 v24, v28, v29
	v_cvt_pk_bf16_f32 v25, v30, v31
	v_cvt_pk_bf16_f32 v26, v34, v35
	v_cvt_pk_bf16_f32 v27, v36, v37
	ds_write_b128 v38, v[24:27] offset:16
	s_nop 1
	v_lshlrev_b32_e32 v24, 16, v20
	v_and_b32_e32 v25, 0xffff0000, v20
	v_lshlrev_b32_e32 v20, 16, v21
	v_and_b32_e32 v21, 0xffff0000, v21
	v_pk_mul_f32 v[26:27], v[122:123], v[20:21] op_sel_hi:[0,1]
	v_lshlrev_b32_e32 v20, 16, v22
	v_and_b32_e32 v21, 0xffff0000, v22
	v_pk_mul_f32 v[28:29], v[122:123], v[20:21] op_sel_hi:[0,1]
	v_lshlrev_b32_e32 v20, 16, v23
	v_and_b32_e32 v21, 0xffff0000, v23
	v_pk_mul_f32 v[24:25], v[122:123], v[24:25] op_sel_hi:[0,1]
	v_pk_mul_f32 v[30:31], v[122:123], v[20:21] op_sel_hi:[0,1]
	v_cvt_pk_bf16_f32 v20, v24, v25
	v_cvt_pk_bf16_f32 v21, v26, v27
	v_cvt_pk_bf16_f32 v22, v28, v29
	v_cvt_pk_bf16_f32 v23, v30, v31
	ds_write_b128 v38, v[20:23] offset:32
	s_nop 1
	v_lshlrev_b32_e32 v20, 16, v16
	v_and_b32_e32 v21, 0xffff0000, v16
	v_lshlrev_b32_e32 v16, 16, v17
	v_and_b32_e32 v17, 0xffff0000, v17
	v_pk_mul_f32 v[22:23], v[122:123], v[16:17] op_sel_hi:[0,1]
	v_lshlrev_b32_e32 v16, 16, v18
	v_and_b32_e32 v17, 0xffff0000, v18
	v_pk_mul_f32 v[24:25], v[122:123], v[16:17] op_sel_hi:[0,1]
	v_lshlrev_b32_e32 v16, 16, v19
	v_and_b32_e32 v17, 0xffff0000, v19
	v_pk_mul_f32 v[20:21], v[122:123], v[20:21] op_sel_hi:[0,1]
	v_pk_mul_f32 v[26:27], v[122:123], v[16:17] op_sel_hi:[0,1]
	v_cvt_pk_bf16_f32 v16, v20, v21
	v_cvt_pk_bf16_f32 v17, v22, v23
	v_cvt_pk_bf16_f32 v18, v24, v25
	v_cvt_pk_bf16_f32 v19, v26, v27
	ds_write_b128 v38, v[16:19] offset:48
	s_nop 1
	v_lshlrev_b32_e32 v16, 16, v12
	v_and_b32_e32 v17, 0xffff0000, v12
	v_lshlrev_b32_e32 v12, 16, v13
	v_and_b32_e32 v13, 0xffff0000, v13
	v_pk_mul_f32 v[18:19], v[122:123], v[12:13] op_sel_hi:[0,1]
	v_lshlrev_b32_e32 v12, 16, v14
	v_and_b32_e32 v13, 0xffff0000, v14
	v_pk_mul_f32 v[20:21], v[122:123], v[12:13] op_sel_hi:[0,1]
	v_lshlrev_b32_e32 v12, 16, v15
	v_and_b32_e32 v13, 0xffff0000, v15
	v_pk_mul_f32 v[16:17], v[122:123], v[16:17] op_sel_hi:[0,1]
	v_pk_mul_f32 v[22:23], v[122:123], v[12:13] op_sel_hi:[0,1]
	v_cvt_pk_bf16_f32 v12, v16, v17
	v_cvt_pk_bf16_f32 v13, v18, v19
	v_cvt_pk_bf16_f32 v14, v20, v21
	v_cvt_pk_bf16_f32 v15, v22, v23
	ds_write_b128 v38, v[12:15] offset:64
	s_nop 1
	v_lshlrev_b32_e32 v12, 16, v8
	v_and_b32_e32 v13, 0xffff0000, v8
	v_lshlrev_b32_e32 v8, 16, v9
	v_and_b32_e32 v9, 0xffff0000, v9
	v_pk_mul_f32 v[14:15], v[122:123], v[8:9] op_sel_hi:[0,1]
	v_lshlrev_b32_e32 v8, 16, v10
	v_and_b32_e32 v9, 0xffff0000, v10
	v_pk_mul_f32 v[16:17], v[122:123], v[8:9] op_sel_hi:[0,1]
	v_lshlrev_b32_e32 v8, 16, v11
	v_and_b32_e32 v9, 0xffff0000, v11
	v_pk_mul_f32 v[12:13], v[122:123], v[12:13] op_sel_hi:[0,1]
	v_pk_mul_f32 v[18:19], v[122:123], v[8:9] op_sel_hi:[0,1]
	v_cvt_pk_bf16_f32 v8, v12, v13
	v_cvt_pk_bf16_f32 v9, v14, v15
	v_cvt_pk_bf16_f32 v10, v16, v17
	v_cvt_pk_bf16_f32 v11, v18, v19
	ds_write_b128 v38, v[8:11] offset:80
	s_nop 1
	v_lshlrev_b32_e32 v8, 16, v4
	v_and_b32_e32 v9, 0xffff0000, v4
	v_lshlrev_b32_e32 v4, 16, v5
	v_and_b32_e32 v5, 0xffff0000, v5
	v_pk_mul_f32 v[10:11], v[122:123], v[4:5] op_sel_hi:[0,1]
	v_lshlrev_b32_e32 v4, 16, v6
	v_and_b32_e32 v5, 0xffff0000, v6
	v_pk_mul_f32 v[12:13], v[122:123], v[4:5] op_sel_hi:[0,1]
	v_lshlrev_b32_e32 v4, 16, v7
	v_and_b32_e32 v5, 0xffff0000, v7
	v_pk_mul_f32 v[8:9], v[122:123], v[8:9] op_sel_hi:[0,1]
	v_pk_mul_f32 v[14:15], v[122:123], v[4:5] op_sel_hi:[0,1]
	v_cvt_pk_bf16_f32 v4, v8, v9
	v_cvt_pk_bf16_f32 v5, v10, v11
	v_cvt_pk_bf16_f32 v6, v12, v13
	v_cvt_pk_bf16_f32 v7, v14, v15
	ds_write_b128 v38, v[4:7] offset:96
	s_nop 1
	v_lshlrev_b32_e32 v4, 16, v0
	v_and_b32_e32 v5, 0xffff0000, v0
	v_lshlrev_b32_e32 v0, 16, v1
	v_and_b32_e32 v1, 0xffff0000, v1
	v_pk_mul_f32 v[6:7], v[122:123], v[0:1] op_sel_hi:[0,1]
	v_lshlrev_b32_e32 v0, 16, v2
	v_and_b32_e32 v1, 0xffff0000, v2
	v_pk_mul_f32 v[8:9], v[122:123], v[0:1] op_sel_hi:[0,1]
	v_lshlrev_b32_e32 v0, 16, v3
	v_and_b32_e32 v1, 0xffff0000, v3
	v_pk_mul_f32 v[4:5], v[122:123], v[4:5] op_sel_hi:[0,1]
	v_pk_mul_f32 v[10:11], v[122:123], v[0:1] op_sel_hi:[0,1]
	v_cvt_pk_bf16_f32 v0, v4, v5
	v_cvt_pk_bf16_f32 v1, v6, v7
	v_cvt_pk_bf16_f32 v2, v8, v9
	v_cvt_pk_bf16_f32 v3, v10, v11
	ds_write_b128 v38, v[0:3] offset:112
	v_readfirstlane_b32 s64, v32
	v_readfirstlane_b32 s65, v33
	v_mbcnt_lo_u32_b32 v34, -1, 0
	v_mbcnt_hi_u32_b32 v34, -1, v34
	v_and_b32_e32 v35, 56, v34
	v_lshlrev_b32_e32 v35, 7, v35
	v_and_b32_e32 v36, 7, v34
	v_lshl_add_u32 v35, v36, 4, v35
	v_add_u32_e32 v35, s57, v35
	v_lshlrev_b32_e32 v37, 4, v34
	ds_read_b128 v[50:53], v35
	ds_read_b128 v[54:57], v35 offset:128
	ds_read_b128 v[58:61], v35 offset:256
	ds_read_b128 v[62:65], v35 offset:384
	s_waitcnt lgkmcnt(0)
	global_store_dwordx4 v37, v[50:53], s[64:65]
	s_add_u32 s64, s64, 0x100000
	s_addc_u32 s65, s65, 0
	global_store_dwordx4 v37, v[54:57], s[64:65]
	s_add_u32 s64, s64, 0x100000
	s_addc_u32 s65, s65, 0
	global_store_dwordx4 v37, v[58:61], s[64:65]
	s_add_u32 s64, s64, 0x100000
	s_addc_u32 s65, s65, 0
	global_store_dwordx4 v37, v[62:65], s[64:65]
	s_add_u32 s64, s64, 0x100000
	s_addc_u32 s65, s65, 0
	ds_read_b128 v[50:53], v35 offset:512
	ds_read_b128 v[54:57], v35 offset:640
	ds_read_b128 v[58:61], v35 offset:768
	ds_read_b128 v[62:65], v35 offset:896
	s_waitcnt lgkmcnt(0)
	global_store_dwordx4 v37, v[50:53], s[64:65]
	s_add_u32 s64, s64, 0x100000
	s_addc_u32 s65, s65, 0
	global_store_dwordx4 v37, v[54:57], s[64:65]
	s_add_u32 s64, s64, 0x100000
	s_addc_u32 s65, s65, 0
	global_store_dwordx4 v37, v[58:61], s[64:65]
	s_add_u32 s64, s64, 0x100000
	s_addc_u32 s65, s65, 0
	global_store_dwordx4 v37, v[62:65], s[64:65]
	s_add_u32 s64, s64, 0x100000
	s_addc_u32 s65, s65, 0
	s_cmpk_lt_i32 s40, 0x100
	s_cbranch_scc1 .LBB0_535
